# GEMM3 epilogue: + DPP row shifts with bound_ctrl zero fill (128 init moves removed) + the 8 row rstd values read from LDS once (27 re-reads with exposed waits become v_mov)
# baseline (speedup 1.0000x reference)
; __device__ __forceinline__ float dpp_shr1(float old, float src) { return __builtin_bit_cast(float, __builtin_amdgcn_update_dpp(__builtin_bit_cast(int, old), __builtin_bit_cast(int, src), 0x111, 0xf, 0xf, false)); }
; __device__ __forceinline__ float dpp_shr2(float old, float src) { return __builtin_bit_cast(float, __builtin_amdgcn_update_dpp(__builtin_bit_cast(int, old), __builtin_bit_cast(int, src), 0x112, 0xf, 0xf, false)); }
; __device__ __forceinline__ float dpp_ror1(float src) { return __builtin_bit_cast(float, __builtin_amdgcn_update_dpp(0, __builtin_bit_cast(int, src), 0x121, 0xf, 0xf, false)); }
;     __device__ __forceinline__ void operator()(const f32x4 (&acc)[2][2][4][2], const Unit& u, int wr, int wc, int fr, int fq) const {
;     ...
;                 for (int m = 0; m < 4; ++m) {
;                     const int r = u.pm * BM + ai * HALF + wr * 64 + m * 16 + fr;
;                     const float rsm = RS[16 * m]; const f32x4 g = acc[ai][0][m][n] * rsm, uu = acc[ai][1][m][n] * rsm; f32x4 p1, p2, av;
;                     if (!sample) {
; #pragma unroll
;                         for (int e = 0; e < 4; ++e) { float o1, o2;
;                             if (m == 0) { o1 = bm1[e]; o2 = (fr == 0) ? bm2[e] : bm1[e]; } else { const float gp = acc[ai][0][m > 0 ? m - 1 : 0][n][e] * RS[16 * (m > 0 ? m - 1 : 0)]; o1 = dpp_ror1(gp); o2 = dpp_ror2(gp); }
;                             p1[e] = dpp_shr1(o1, g[e]); p2[e] = dpp_shr2(o2, g[e]); }
;                         if (ai == 0 && wr == 0 && m == 0 && fr < 2 && (u.pm & 7) != 0) {
;                             *(f32x4*)(fix + ((size_t)(72 + u.pm * 2 + fr)) * DFF + j0 + 4 * n) = g; *(f32x4*)(fix + ((size_t)(144 + u.pm * 2 + fr)) * DFF + j0 + 4 * n) = uu; }
;                     } else {
;                         const int t = fr & 7, bs = (r - MP) >> 3; f32x4 s0 = (f32x4){0.f, 0.f, 0.f, 0.f}, s1 = s0;
;                         if (t < 2) { s0 = *(const f32x4*)(st_ffn + ((size_t)bs * 2 + 0) * DFF + j0 + 4 * n); s1 = *(const f32x4*)(st_ffn + ((size_t)bs * 2 + 1) * DFF + j0 + 4 * n); }
; #pragma unroll
;                         for (int e = 0; e < 4; ++e) { const float a1 = dpp_shr1(0.f, g[e]), a2 = dpp_shr2(0.f, g[e]); p1[e] = (t >= 1) ? a1 : s1[e]; p2[e] = (t >= 2) ? a2 : (t == 1 ? s1[e] : s0[e]); }
.LBB0_747:
	s_or_b64 exec, exec, s[6:7]
	v_lshl_add_u32 v187, v186, 2, s28
	ds_read_b32 v188, v187
	ds_read_b32 v237, v187
	ds_read_b32 v238, v187 offset:64
	ds_read_b32 v239, v187 offset:128
	ds_read_b32 v240, v187 offset:192
	ds_read_b32 v241, v187 offset:512
	ds_read_b32 v242, v187 offset:576
	ds_read_b32 v243, v187 offset:640
	ds_read_b32 v244, v187 offset:704
	v_and_b32_e32 v150, 7, v186
	v_add_u32_e32 v217, s97, v186
	v_cmp_gt_u32_e64 s[14:15], 2, v150
	v_ashrrev_i32_e32 v185, 31, v184
	v_cmp_eq_u32_e64 s[10:11], 0, v150
	v_cmp_lt_u32_e64 s[6:7], 1, v150
	v_cmp_eq_u32_e64 s[8:9], 1, v150
	v_cmp_lt_u32_e64 s[12:13], 5, v150
	v_add_u32_e32 v178, -6, v150
	v_cmp_eq_u32_e64 s[18:19], 0, v186
	v_cmp_lt_i32_e64 s[20:21], 1, v186
	s_waitcnt lgkmcnt(0)
	v_pk_mul_f32 v[152:153], v[148:149], v[188:189] op_sel_hi:[1,0]
	v_pk_mul_f32 v[150:151], v[146:147], v[188:189] op_sel_hi:[1,0]
	s_and_b64 vcc, exec, s[22:23]
	s_cbranch_vccz .LBB0_753
	s_add_i32 s16, s74, 0xffffe000
	v_add_u32_e32 v162, s16, v217
	v_ashrrev_i32_e32 v192, 3, v162
	v_mov_b32_e32 v162, 0
	v_mov_b32_e32 v163, 0
	v_mov_b32_e32 v164, 0
	v_mov_b32_e32 v165, 0
	v_mov_b32_e32 v166, 0
	v_mov_b32_e32 v167, 0
	v_mov_b32_e32 v168, 0
	v_mov_b32_e32 v169, 0
	s_and_saveexec_b64 s[16:17], s[14:15]
	s_cbranch_execz .LBB0_750
	v_mov_b64_e32 v[162:163], s[36:37]
	v_mad_i64_i32 v[162:163], s[82:83], v192, s53, v[162:163]
	v_lshl_add_u64 v[162:163], v[184:185], 2, v[162:163]
	v_add_co_u32_e32 v166, vcc, 0xa000, v162
	s_nop 1
	v_addc_co_u32_e32 v167, vcc, 0, v163, vcc
	s_mov_b64 s[98:99], 0x2b000
	v_lshl_add_u64 v[246:247], v[162:163], 0, s[98:99]
	global_load_dword v248, v[246:247], off
	s_mov_b64 s[98:99], 0x35c00
	v_lshl_add_u64 v[246:247], v[162:163], 0, s[98:99]
	global_load_dword v248, v[246:247], off
	s_mov_b64 s[98:99], 0x56000
	v_lshl_add_u64 v[246:247], v[162:163], 0, s[98:99]
	global_load_dword v248, v[246:247], off
	s_mov_b64 s[98:99], 0x60c00
	v_lshl_add_u64 v[246:247], v[162:163], 0, s[98:99]
	global_load_dword v248, v[246:247], off
	s_mov_b64 s[98:99], 0x81000
	v_lshl_add_u64 v[246:247], v[162:163], 0, s[98:99]
	global_load_dword v248, v[246:247], off
	s_mov_b64 s[98:99], 0x8bc00
	v_lshl_add_u64 v[246:247], v[162:163], 0, s[98:99]
	global_load_dword v248, v[246:247], off
	s_mov_b64 s[98:99], 0x158000
	v_lshl_add_u64 v[246:247], v[162:163], 0, s[98:99]
	global_load_dword v248, v[246:247], off
	s_mov_b64 s[98:99], 0x162c00
	v_lshl_add_u64 v[246:247], v[162:163], 0, s[98:99]
	global_load_dword v248, v[246:247], off
	s_mov_b64 s[98:99], 0x183000
	v_lshl_add_u64 v[246:247], v[162:163], 0, s[98:99]
	global_load_dword v248, v[246:247], off
	s_mov_b64 s[98:99], 0x18dc00
	v_lshl_add_u64 v[246:247], v[162:163], 0, s[98:99]
	global_load_dword v248, v[246:247], off
	s_mov_b64 s[98:99], 0x1ae000
	v_lshl_add_u64 v[246:247], v[162:163], 0, s[98:99]
	global_load_dword v248, v[246:247], off
	s_mov_b64 s[98:99], 0x1b8c00
	v_lshl_add_u64 v[246:247], v[162:163], 0, s[98:99]
	global_load_dword v248, v[246:247], off
	s_mov_b64 s[98:99], 0x1d9000
	v_lshl_add_u64 v[246:247], v[162:163], 0, s[98:99]
	global_load_dword v248, v[246:247], off
	s_mov_b64 s[98:99], 0x1e3c00
	v_lshl_add_u64 v[246:247], v[162:163], 0, s[98:99]
	global_load_dword v248, v[246:247], off
	global_load_dwordx4 v[162:165], v[162:163], off
	s_nop 0
	global_load_dwordx4 v[166:169], v[166:167], off offset:3072
.LBB0_750:
	s_or_b64 exec, exec, s[16:17]
	v_mov_b32_dpp v222, v150 row_shr:1 row_mask:0xf bank_mask:0xf bound_ctrl:1
	v_mov_b32_dpp v223, v150 row_shr:2 row_mask:0xf bank_mask:0xf bound_ctrl:1
	v_mov_b32_dpp v224, v151 row_shr:1 row_mask:0xf bank_mask:0xf bound_ctrl:1
	v_mov_b32_dpp v225, v151 row_shr:2 row_mask:0xf bank_mask:0xf bound_ctrl:1
	v_mov_b32_dpp v226, v152 row_shr:1 row_mask:0xf bank_mask:0xf bound_ctrl:1
	v_mov_b32_dpp v227, v152 row_shr:2 row_mask:0xf bank_mask:0xf bound_ctrl:1
	v_mov_b32_dpp v228, v153 row_shr:1 row_mask:0xf bank_mask:0xf bound_ctrl:1
	v_mov_b32_dpp v229, v153 row_shr:2 row_mask:0xf bank_mask:0xf bound_ctrl:1
	s_mov_b64 s[82:83], 0
	s_mov_b64 s[16:17], 0
	s_and_saveexec_b64 s[84:85], s[12:13]
	s_xor_b64 s[84:85], exec, s[84:85]
	v_ashrrev_i32_e32 v193, 31, v192
	s_mov_b64 s[16:17], exec
	v_lshl_add_u64 v[190:191], v[192:193], 1, v[178:179]
	s_or_b64 exec, exec, s[84:85]
	s_waitcnt vmcnt(0)
	v_cndmask_b32_e64 v162, v162, v166, s[8:9]
	v_cndmask_b32_e64 v163, v163, v167, s[8:9]
	v_cndmask_b32_e64 v164, v164, v168, s[8:9]
	v_cndmask_b32_e64 v165, v165, v169, s[8:9]
	v_cndmask_b32_e64 v192, v222, v166, s[10:11]
	v_cndmask_b32_e64 v162, v162, v223, s[6:7]
	v_cndmask_b32_e64 v193, v224, v167, s[10:11]
	v_cndmask_b32_e64 v163, v163, v225, s[6:7]
	v_cndmask_b32_e64 v222, v226, v168, s[10:11]
	v_cndmask_b32_e64 v164, v164, v227, s[6:7]
	v_cndmask_b32_e64 v168, v228, v169, s[10:11]
	v_cndmask_b32_e64 v167, v165, v229, s[6:7]
	s_branch .LBB0_754

; __device__ __forceinline__ unsigned cvt_pk_bf16(float lo, float hi) { unsigned r; asm volatile("v_cvt_pk_bf16_f32 %0, %1, %2" : "=v"(r) : "v"(lo), "v"(hi)); return r; }
;     __device__ __forceinline__ void operator()(const f32x4 (&acc)[2][2][4][2], const Unit& u, int wr, int wc, int fr, int fq) const {
;     ...
;                     const float rsm = RS[16 * m]; const f32x4 g = acc[ai][0][m][n] * rsm, uu = acc[ai][1][m][n] * rsm; f32x4 p1, p2, av;
;                     if (!sample) {
; #pragma unroll
;                         for (int e = 0; e < 4; ++e) { float o1, o2;
;                             if (m == 0) { o1 = bm1[e]; o2 = (fr == 0) ? bm2[e] : bm1[e]; } else { const float gp = acc[ai][0][m > 0 ? m - 1 : 0][n][e] * RS[16 * (m > 0 ? m - 1 : 0)]; o1 = dpp_ror1(gp); o2 = dpp_ror2(gp); }
;                             p1[e] = dpp_shr1(o1, g[e]); p2[e] = dpp_shr2(o2, g[e]); }
;                         if (ai == 0 && wr == 0 && m == 0 && fr < 2 && (u.pm & 7) != 0) {
;                             *(f32x4*)(fix + ((size_t)(72 + u.pm * 2 + fr)) * DFF + j0 + 4 * n) = g; *(f32x4*)(fix + ((size_t)(144 + u.pm * 2 + fr)) * DFF + j0 + 4 * n) = uu; }
;                     } else {
;                         const int t = fr & 7, bs = (r - MP) >> 3; f32x4 s0 = (f32x4){0.f, 0.f, 0.f, 0.f}, s1 = s0;
;                         if (t < 2) { s0 = *(const f32x4*)(st_ffn + ((size_t)bs * 2 + 0) * DFF + j0 + 4 * n); s1 = *(const f32x4*)(st_ffn + ((size_t)bs * 2 + 1) * DFF + j0 + 4 * n); }
; #pragma unroll
;                         for (int e = 0; e < 4; ++e) { const float a1 = dpp_shr1(0.f, g[e]), a2 = dpp_shr2(0.f, g[e]); p1[e] = (t >= 1) ? a1 : s1[e]; p2[e] = (t >= 2) ? a2 : (t == 1 ? s1[e] : s0[e]); }
;                         if (t >= 6) *(f32x4*)(out + O_SFFN + ((size_t)bs * 2 + (t - 6)) * DFF + j0 + 4 * n) = g;
;                     }
;                     const f32x4 gc = bb + w0 * p2 + w1 * p1 + w2 * g;
; #pragma unroll
;                     for (int e = 0; e < 4; ++e) av[e] = silu_e(gc[e]) * uu[e];
;                     if (n == 0) { keep[ai][m].x = cvt_pk_bf16(av[0], av[1]); keep[ai][m].y = cvt_pk_bf16(av[2], av[3]); }
;                     else { u32x4e w; w.x = keep[ai][m].x; w.y = keep[ai][m].y; w.z = cvt_pk_bf16(av[0], av[1]); w.w = cvt_pk_bf16(av[2], av[3]); *(u32x4e*)(ACT + act_off(r, j0)) = w; }
.LBB0_760:
	s_or_b64 exec, exec, s[84:85]
	v_fma_f32 v154, v141, v167, v129
	v_fmac_f32_e32 v154, v137, v168
	v_fmac_f32_e32 v154, v133, v153
	v_mul_f32_e32 v153, 0xbfb8aa3b, v154
	v_exp_f32_e32 v153, v153
	v_fma_f32 v155, v140, v164, v128
	v_fmac_f32_e32 v155, v136, v222
	v_fmac_f32_e32 v155, v132, v152
	v_add_f32_e32 v152, 1.0, v153
	v_mul_f32_e32 v153, 0xbfb8aa3b, v155
	v_exp_f32_e32 v153, v153
	v_rcp_f32_e32 v152, v152
	v_add_u32_e32 v164, 16, v217
	s_andn2_b64 vcc, exec, s[22:23]
	v_add_f32_e32 v153, 1.0, v153
	v_mul_f32_e32 v152, v154, v152
	v_mul_f32_e32 v121, v121, v152
	v_rcp_f32_e32 v152, v153
	v_fma_f32 v153, v139, v163, v127
	v_fmac_f32_e32 v153, v135, v193
	v_fma_f32 v154, v138, v162, v126
	v_fmac_f32_e32 v153, v131, v151
	v_fmac_f32_e32 v154, v134, v192
	v_mul_f32_e32 v151, 0xbfb8aa3b, v153
	v_fmac_f32_e32 v154, v130, v150
	v_exp_f32_e32 v151, v151
	v_mul_f32_e32 v150, 0xbfb8aa3b, v154
	v_exp_f32_e32 v150, v150
	v_mul_f32_e32 v152, v155, v152
	v_add_f32_e32 v151, 1.0, v151
	v_rcp_f32_e32 v151, v151
	v_add_f32_e32 v150, 1.0, v150
	v_rcp_f32_e32 v150, v150
	v_mul_f32_e32 v152, v120, v152
	v_mul_f32_e32 v120, v153, v151
	v_mul_f32_e32 v119, v119, v120
	v_mul_f32_e32 v120, v154, v150
	v_mul_f32_e32 v118, v118, v120
	v_cvt_pk_bf16_f32 v120, v118, v119
	v_cvt_pk_bf16_f32 v121, v152, v121
	v_mov_b32_e32 v118, v238
	s_waitcnt lgkmcnt(0)
	v_pk_mul_f32 v[152:153], v[124:125], v[118:119] op_sel_hi:[1,0]
	v_pk_mul_f32 v[150:151], v[122:123], v[118:119] op_sel_hi:[1,0]
	v_cndmask_b32_e64 v119, 0, 1, s[22:23]
	v_cmp_ne_u32_e64 s[16:17], 1, v119
	s_mov_b64 s[22:23], -1
	s_cbranch_vccnz .LBB0_766
	s_add_i32 s22, s74, 0xffffe000
	v_add_u32_e32 v119, s22, v164
	v_ashrrev_i32_e32 v162, 3, v119
	v_mov_b32_e32 v154, 0
	v_mov_b32_e32 v155, 0
	v_mov_b32_e32 v156, 0
	v_mov_b32_e32 v157, 0
	v_mov_b32_e32 v158, 0
	v_mov_b32_e32 v159, 0
	v_mov_b32_e32 v160, 0
	v_mov_b32_e32 v161, 0
	s_and_saveexec_b64 s[22:23], s[14:15]
	s_cbranch_execz .LBB0_763
	v_mov_b64_e32 v[154:155], s[36:37]
	v_mad_i64_i32 v[154:155], s[82:83], v162, s53, v[154:155]
	v_lshl_add_u64 v[154:155], v[184:185], 2, v[154:155]
	v_add_co_u32_e32 v158, vcc, 0xa000, v154
	s_nop 1
	v_addc_co_u32_e32 v159, vcc, 0, v155, vcc
	global_load_dwordx4 v[154:157], v[154:155], off
	s_nop 0
	global_load_dwordx4 v[158:161], v[158:159], off offset:3072
.LBB0_763:
	s_or_b64 exec, exec, s[22:23]
	v_mov_b32_dpp v119, v150 row_shr:1 row_mask:0xf bank_mask:0xf bound_ctrl:1
	v_mov_b32_dpp v167, v150 row_shr:2 row_mask:0xf bank_mask:0xf bound_ctrl:1
	v_mov_b32_dpp v168, v151 row_shr:1 row_mask:0xf bank_mask:0xf bound_ctrl:1
	v_mov_b32_dpp v169, v151 row_shr:2 row_mask:0xf bank_mask:0xf bound_ctrl:1
	v_mov_b32_dpp v188, v152 row_shr:1 row_mask:0xf bank_mask:0xf bound_ctrl:1
	v_mov_b32_dpp v190, v152 row_shr:2 row_mask:0xf bank_mask:0xf bound_ctrl:1
	v_mov_b32_dpp v191, v153 row_shr:1 row_mask:0xf bank_mask:0xf bound_ctrl:1
	v_mov_b32_dpp v192, v153 row_shr:2 row_mask:0xf bank_mask:0xf bound_ctrl:1
	s_and_saveexec_b64 s[22:23], s[12:13]
	s_cbranch_execz .LBB0_765
	v_ashrrev_i32_e32 v163, 31, v162
	v_lshl_add_u64 v[162:163], v[162:163], 1, v[178:179]
	v_mov_b64_e32 v[222:223], s[62:63]
	v_mad_u64_u32 v[222:223], s[82:83], v162, s26, v[222:223]
	v_mad_i32_i24 v223, v163, s26, v223
	v_lshl_add_u64 v[162:163], v[184:185], 2, v[222:223]
	global_store_dwordx4 v[162:163], v[150:153], off

; __device__ __forceinline__ unsigned cvt_pk_bf16(float lo, float hi) { unsigned r; asm volatile("v_cvt_pk_bf16_f32 %0, %1, %2" : "=v"(r) : "v"(lo), "v"(hi)); return r; }
;     __device__ __forceinline__ void operator()(const f32x4 (&acc)[2][2][4][2], const Unit& u, int wr, int wc, int fr, int fq) const {
;     ...
;                     const float rsm = RS[16 * m]; const f32x4 g = acc[ai][0][m][n] * rsm, uu = acc[ai][1][m][n] * rsm; f32x4 p1, p2, av;
;                     if (!sample) {
; #pragma unroll
;                         for (int e = 0; e < 4; ++e) { float o1, o2;
;                             if (m == 0) { o1 = bm1[e]; o2 = (fr == 0) ? bm2[e] : bm1[e]; } else { const float gp = acc[ai][0][m > 0 ? m - 1 : 0][n][e] * RS[16 * (m > 0 ? m - 1 : 0)]; o1 = dpp_ror1(gp); o2 = dpp_ror2(gp); }
;                             p1[e] = dpp_shr1(o1, g[e]); p2[e] = dpp_shr2(o2, g[e]); }
;                         if (ai == 0 && wr == 0 && m == 0 && fr < 2 && (u.pm & 7) != 0) {
;                             *(f32x4*)(fix + ((size_t)(72 + u.pm * 2 + fr)) * DFF + j0 + 4 * n) = g; *(f32x4*)(fix + ((size_t)(144 + u.pm * 2 + fr)) * DFF + j0 + 4 * n) = uu; }
;                     } else {
;                         const int t = fr & 7, bs = (r - MP) >> 3; f32x4 s0 = (f32x4){0.f, 0.f, 0.f, 0.f}, s1 = s0;
;                         if (t < 2) { s0 = *(const f32x4*)(st_ffn + ((size_t)bs * 2 + 0) * DFF + j0 + 4 * n); s1 = *(const f32x4*)(st_ffn + ((size_t)bs * 2 + 1) * DFF + j0 + 4 * n); }
; #pragma unroll
;                         for (int e = 0; e < 4; ++e) { const float a1 = dpp_shr1(0.f, g[e]), a2 = dpp_shr2(0.f, g[e]); p1[e] = (t >= 1) ? a1 : s1[e]; p2[e] = (t >= 2) ? a2 : (t == 1 ? s1[e] : s0[e]); }
;                         if (t >= 6) *(f32x4*)(out + O_SFFN + ((size_t)bs * 2 + (t - 6)) * DFF + j0 + 4 * n) = g;
;                     }
;                     const f32x4 gc = bb + w0 * p2 + w1 * p1 + w2 * g;
; #pragma unroll
;                     for (int e = 0; e < 4; ++e) av[e] = silu_e(gc[e]) * uu[e];
;                     if (n == 0) { keep[ai][m].x = cvt_pk_bf16(av[0], av[1]); keep[ai][m].y = cvt_pk_bf16(av[2], av[3]); }
;                     else { u32x4e w; w.x = keep[ai][m].x; w.y = keep[ai][m].y; w.z = cvt_pk_bf16(av[0], av[1]); w.w = cvt_pk_bf16(av[2], av[3]); *(u32x4e*)(ACT + act_off(r, j0)) = w; }
.LBB0_766:
	s_and_b64 vcc, exec, s[22:23]
	s_cbranch_vccz .LBB0_768
	v_mov_b32_e32 v119, v237
	v_mov_b32_e32 v162, v179
	v_mov_b32_e32 v154, v179
	v_mov_b32_e32 v158, v179
	v_mov_b32_e32 v155, v179
	s_waitcnt lgkmcnt(0)
	v_mul_f32_e32 v146, v146, v119
	v_mov_b32_e32 v159, v179
	v_mov_b32_e32 v156, v179
	v_mov_b32_dpp v162, v146 row_ror:1 row_mask:0xf bank_mask:0xf
	v_mov_b32_dpp v154, v146 row_ror:2 row_mask:0xf bank_mask:0xf
	v_mul_f32_e32 v146, v147, v119
	v_mov_b32_e32 v160, v179
	v_mov_b32_e32 v157, v179
	v_mov_b32_dpp v158, v146 row_ror:1 row_mask:0xf bank_mask:0xf
	v_mov_b32_dpp v155, v146 row_ror:2 row_mask:0xf bank_mask:0xf
	v_mul_f32_e32 v146, v148, v119
	v_mul_f32_e32 v119, v149, v119
	v_mov_b32_dpp v162, v150 row_shr:1 row_mask:0xf bank_mask:0xf
	v_mov_b32_dpp v159, v146 row_ror:1 row_mask:0xf bank_mask:0xf
	v_mov_b32_dpp v156, v146 row_ror:2 row_mask:0xf bank_mask:0xf
	v_mov_b32_dpp v160, v119 row_ror:1 row_mask:0xf bank_mask:0xf
	v_mov_b32_dpp v157, v119 row_ror:2 row_mask:0xf bank_mask:0xf
	v_mov_b32_dpp v154, v150 row_shr:2 row_mask:0xf bank_mask:0xf
	v_mov_b32_dpp v158, v151 row_shr:1 row_mask:0xf bank_mask:0xf
	v_mov_b32_dpp v155, v151 row_shr:2 row_mask:0xf bank_mask:0xf
	v_mov_b32_dpp v159, v152 row_shr:1 row_mask:0xf bank_mask:0xf
	v_mov_b32_dpp v156, v152 row_shr:2 row_mask:0xf bank_mask:0xf
	v_mov_b32_dpp v160, v153 row_shr:1 row_mask:0xf bank_mask:0xf
	v_mov_b32_dpp v157, v153 row_shr:2 row_mask:0xf bank_mask:0xf
.LBB0_768:
	v_fma_f32 v148, v141, v157, v129
	v_fmac_f32_e32 v148, v137, v160
	v_fmac_f32_e32 v148, v133, v153
	v_mul_f32_e32 v146, 0xbfb8aa3b, v148
	v_exp_f32_e32 v149, v146
	v_mov_b32_e32 v146, v118
	v_mov_b32_e32 v147, v118
	v_pk_mul_f32 v[144:145], v[144:145], v[146:147]
	v_add_f32_e32 v146, 1.0, v149
	v_rcp_f32_e32 v146, v146
	v_fma_f32 v147, v140, v156, v128
	v_fmac_f32_e32 v147, v136, v159
	v_mov_b32_e32 v119, v118
	v_fmac_f32_e32 v147, v132, v152
	v_mul_f32_e32 v149, 0xbfb8aa3b, v147
	v_pk_mul_f32 v[118:119], v[142:143], v[118:119]
	v_mul_f32_e32 v142, v148, v146
	v_exp_f32_e32 v149, v149
	v_mul_f32_e32 v142, v145, v142
	v_fma_f32 v145, v139, v155, v127
	v_fmac_f32_e32 v145, v135, v158
	v_fma_f32 v148, v138, v154, v126
	v_fmac_f32_e32 v145, v131, v151
	v_fmac_f32_e32 v148, v134, v162
	v_mul_f32_e32 v146, 0xbfb8aa3b, v145
	v_fmac_f32_e32 v148, v130, v150
	v_add_f32_e32 v143, 1.0, v149
	v_exp_f32_e32 v146, v146
	v_mul_f32_e32 v149, 0xbfb8aa3b, v148
	v_rcp_f32_e32 v143, v143
	v_exp_f32_e32 v149, v149
	v_add_f32_e32 v146, 1.0, v146
	v_rcp_f32_e32 v146, v146
	v_mul_f32_e32 v143, v147, v143
	v_add_f32_e32 v147, 1.0, v149
	v_rcp_f32_e32 v147, v147
	v_mul_f32_e32 v143, v144, v143
	v_mul_f32_e32 v144, v145, v146
	v_mul_f32_e32 v119, v119, v144
	v_mul_f32_e32 v144, v148, v147
	v_mul_f32_e32 v118, v118, v144
	v_cvt_pk_bf16_f32 v118, v118, v119
	v_cvt_pk_bf16_f32 v119, v143, v142
	v_mov_b32_e32 v154, v239
	v_add_u32_e32 v158, 32, v217
	s_and_b64 vcc, exec, s[16:17]
	s_mov_b64 s[22:23], -1
	s_waitcnt lgkmcnt(0)
	v_pk_mul_f32 v[144:145], v[108:109], v[154:155] op_sel_hi:[1,0]
	v_pk_mul_f32 v[142:143], v[106:107], v[154:155] op_sel_hi:[1,0]
	s_cbranch_vccnz .LBB0_774
	s_add_i32 s22, s74, 0xffffe000
	v_add_u32_e32 v146, s22, v158
	v_ashrrev_i32_e32 v156, 3, v146
	v_mov_b32_e32 v146, 0
	v_mov_b32_e32 v147, 0
	v_mov_b32_e32 v148, 0
	v_mov_b32_e32 v149, 0
	v_mov_b32_e32 v150, 0
	v_mov_b32_e32 v151, 0
	v_mov_b32_e32 v152, 0
	v_mov_b32_e32 v153, 0
	s_and_saveexec_b64 s[22:23], s[14:15]
	s_cbranch_execz .LBB0_771
	v_mov_b64_e32 v[146:147], s[36:37]
	v_mad_i64_i32 v[146:147], s[82:83], v156, s53, v[146:147]
	v_lshl_add_u64 v[146:147], v[184:185], 2, v[146:147]
	v_add_co_u32_e32 v150, vcc, 0xa000, v146
	s_nop 1
	v_addc_co_u32_e32 v151, vcc, 0, v147, vcc
	global_load_dwordx4 v[146:149], v[146:147], off
	s_nop 0
	global_load_dwordx4 v[150:153], v[150:151], off offset:3072
.LBB0_771:
	s_or_b64 exec, exec, s[22:23]
	v_mov_b32_dpp v155, v142 row_shr:1 row_mask:0xf bank_mask:0xf bound_ctrl:1
	v_mov_b32_dpp v159, v142 row_shr:2 row_mask:0xf bank_mask:0xf bound_ctrl:1
	v_mov_b32_dpp v160, v143 row_shr:1 row_mask:0xf bank_mask:0xf bound_ctrl:1
	v_mov_b32_dpp v161, v143 row_shr:2 row_mask:0xf bank_mask:0xf bound_ctrl:1
	v_mov_b32_dpp v162, v144 row_shr:1 row_mask:0xf bank_mask:0xf bound_ctrl:1
	v_mov_b32_dpp v163, v144 row_shr:2 row_mask:0xf bank_mask:0xf bound_ctrl:1
	v_mov_b32_dpp v167, v145 row_shr:1 row_mask:0xf bank_mask:0xf bound_ctrl:1
	v_mov_b32_dpp v168, v145 row_shr:2 row_mask:0xf bank_mask:0xf bound_ctrl:1
	s_and_saveexec_b64 s[22:23], s[12:13]
	s_cbranch_execz .LBB0_773
	v_ashrrev_i32_e32 v157, 31, v156
	v_lshl_add_u64 v[156:157], v[156:157], 1, v[178:179]
	v_mov_b64_e32 v[190:191], s[62:63]
	v_mad_u64_u32 v[190:191], s[82:83], v156, s26, v[190:191]
	v_mad_i32_i24 v191, v157, s26, v191
	v_lshl_add_u64 v[156:157], v[184:185], 2, v[190:191]
	global_store_dwordx4 v[156:157], v[142:145], off

; __device__ __forceinline__ unsigned cvt_pk_bf16(float lo, float hi) { unsigned r; asm volatile("v_cvt_pk_bf16_f32 %0, %1, %2" : "=v"(r) : "v"(lo), "v"(hi)); return r; }
;     __device__ __forceinline__ void operator()(const f32x4 (&acc)[2][2][4][2], const Unit& u, int wr, int wc, int fr, int fq) const {
;     ...
;                     const float rsm = RS[16 * m]; const f32x4 g = acc[ai][0][m][n] * rsm, uu = acc[ai][1][m][n] * rsm; f32x4 p1, p2, av;
;                     if (!sample) {
; #pragma unroll
;                         for (int e = 0; e < 4; ++e) { float o1, o2;
;                             if (m == 0) { o1 = bm1[e]; o2 = (fr == 0) ? bm2[e] : bm1[e]; } else { const float gp = acc[ai][0][m > 0 ? m - 1 : 0][n][e] * RS[16 * (m > 0 ? m - 1 : 0)]; o1 = dpp_ror1(gp); o2 = dpp_ror2(gp); }
;                             p1[e] = dpp_shr1(o1, g[e]); p2[e] = dpp_shr2(o2, g[e]); }
;                         if (ai == 0 && wr == 0 && m == 0 && fr < 2 && (u.pm & 7) != 0) {
;                             *(f32x4*)(fix + ((size_t)(72 + u.pm * 2 + fr)) * DFF + j0 + 4 * n) = g; *(f32x4*)(fix + ((size_t)(144 + u.pm * 2 + fr)) * DFF + j0 + 4 * n) = uu; }
;                     } else {
;                         const int t = fr & 7, bs = (r - MP) >> 3; f32x4 s0 = (f32x4){0.f, 0.f, 0.f, 0.f}, s1 = s0;
;                         if (t < 2) { s0 = *(const f32x4*)(st_ffn + ((size_t)bs * 2 + 0) * DFF + j0 + 4 * n); s1 = *(const f32x4*)(st_ffn + ((size_t)bs * 2 + 1) * DFF + j0 + 4 * n); }
; #pragma unroll
;                         for (int e = 0; e < 4; ++e) { const float a1 = dpp_shr1(0.f, g[e]), a2 = dpp_shr2(0.f, g[e]); p1[e] = (t >= 1) ? a1 : s1[e]; p2[e] = (t >= 2) ? a2 : (t == 1 ? s1[e] : s0[e]); }
;                         if (t >= 6) *(f32x4*)(out + O_SFFN + ((size_t)bs * 2 + (t - 6)) * DFF + j0 + 4 * n) = g;
;                     }
;                     const f32x4 gc = bb + w0 * p2 + w1 * p1 + w2 * g;
; #pragma unroll
;                     for (int e = 0; e < 4; ++e) av[e] = silu_e(gc[e]) * uu[e];
;                     if (n == 0) { keep[ai][m].x = cvt_pk_bf16(av[0], av[1]); keep[ai][m].y = cvt_pk_bf16(av[2], av[3]); }
;                     else { u32x4e w; w.x = keep[ai][m].x; w.y = keep[ai][m].y; w.z = cvt_pk_bf16(av[0], av[1]); w.w = cvt_pk_bf16(av[2], av[3]); *(u32x4e*)(ACT + act_off(r, j0)) = w; }
.LBB0_774:
	s_and_b64 vcc, exec, s[22:23]
	s_cbranch_vccz .LBB0_776
	v_mov_b32_e32 v149, v238
	v_mov_b32_e32 v156, v179
	v_mov_b32_e32 v146, v179
	v_mov_b32_e32 v150, v179
	v_mov_b32_e32 v147, v179
	s_waitcnt lgkmcnt(0)
	v_mul_f32_e32 v122, v122, v149
	v_mov_b32_e32 v151, v179
	v_mov_b32_e32 v148, v179
	v_mov_b32_dpp v156, v122 row_ror:1 row_mask:0xf bank_mask:0xf
	v_mov_b32_dpp v146, v122 row_ror:2 row_mask:0xf bank_mask:0xf
	v_mul_f32_e32 v122, v123, v149
	v_mov_b32_e32 v152, v179
	v_mov_b32_dpp v156, v142 row_shr:1 row_mask:0xf bank_mask:0xf
	v_mov_b32_dpp v150, v122 row_ror:1 row_mask:0xf bank_mask:0xf
	v_mov_b32_dpp v147, v122 row_ror:2 row_mask:0xf bank_mask:0xf
	v_mul_f32_e32 v122, v124, v149
	v_mov_b32_dpp v146, v142 row_shr:2 row_mask:0xf bank_mask:0xf
	v_mov_b32_dpp v150, v143 row_shr:1 row_mask:0xf bank_mask:0xf
	v_mov_b32_dpp v151, v122 row_ror:1 row_mask:0xf bank_mask:0xf
	v_mov_b32_dpp v148, v122 row_ror:2 row_mask:0xf bank_mask:0xf
	v_mul_f32_e32 v122, v125, v149
	v_mov_b32_e32 v149, v179
	v_mov_b32_dpp v147, v143 row_shr:2 row_mask:0xf bank_mask:0xf
	v_mov_b32_dpp v152, v122 row_ror:1 row_mask:0xf bank_mask:0xf
	v_mov_b32_dpp v149, v122 row_ror:2 row_mask:0xf bank_mask:0xf
	v_mov_b32_dpp v151, v144 row_shr:1 row_mask:0xf bank_mask:0xf
	v_mov_b32_dpp v148, v144 row_shr:2 row_mask:0xf bank_mask:0xf
	v_mov_b32_dpp v152, v145 row_shr:1 row_mask:0xf bank_mask:0xf
	v_mov_b32_dpp v149, v145 row_shr:2 row_mask:0xf bank_mask:0xf
.LBB0_776:
	v_fma_f32 v124, v141, v149, v129
	v_fmac_f32_e32 v124, v137, v152
	v_fmac_f32_e32 v124, v133, v145
	v_mul_f32_e32 v122, 0xbfb8aa3b, v124
	v_exp_f32_e32 v125, v122
	v_mov_b32_e32 v122, v154
	v_mov_b32_e32 v123, v154
	v_pk_mul_f32 v[116:117], v[116:117], v[122:123]
	v_add_f32_e32 v122, 1.0, v125
	v_rcp_f32_e32 v122, v122
	v_fma_f32 v123, v140, v148, v128
	v_fmac_f32_e32 v123, v136, v151
	v_fmac_f32_e32 v123, v132, v144
	v_mul_f32_e32 v125, 0xbfb8aa3b, v123
	v_exp_f32_e32 v125, v125
	v_mul_f32_e32 v122, v124, v122
	v_fma_f32 v124, v139, v147, v127
	v_fmac_f32_e32 v124, v135, v150
	v_fmac_f32_e32 v124, v131, v143
	v_fma_f32 v143, v138, v146, v126
	v_fmac_f32_e32 v143, v134, v156
	v_mul_f32_e32 v117, v117, v122
	v_add_f32_e32 v122, 1.0, v125
	v_mul_f32_e32 v125, 0xbfb8aa3b, v124
	v_fmac_f32_e32 v143, v130, v142
	v_rcp_f32_e32 v122, v122
	v_exp_f32_e32 v125, v125
	v_mul_f32_e32 v142, 0xbfb8aa3b, v143
	v_exp_f32_e32 v142, v142
	v_mul_f32_e32 v122, v123, v122
	v_add_f32_e32 v123, 1.0, v125
	v_rcp_f32_e32 v123, v123
	v_add_f32_e32 v125, 1.0, v142
	v_rcp_f32_e32 v125, v125
	v_mov_b32_e32 v155, v154
	v_pk_mul_f32 v[114:115], v[114:115], v[154:155]
	v_mul_f32_e32 v116, v116, v122
	v_mul_f32_e32 v122, v124, v123
	v_mul_f32_e32 v115, v115, v122
	v_mul_f32_e32 v122, v143, v125
	v_mul_f32_e32 v114, v114, v122
	v_cvt_pk_bf16_f32 v114, v114, v115
	v_cvt_pk_bf16_f32 v115, v116, v117
	v_mov_b32_e32 v116, v240
	v_add_u32_e32 v152, 48, v217
	s_and_b64 vcc, exec, s[16:17]
	s_mov_b64 s[22:23], -1
	s_waitcnt lgkmcnt(0)
	v_pk_mul_f32 v[112:113], v[112:113], v[116:117] op_sel_hi:[1,0]
	v_pk_mul_f32 v[110:111], v[110:111], v[116:117] op_sel_hi:[1,0]
	s_cbranch_vccnz .LBB0_782
	s_add_i32 s22, s74, 0xffffe000
	v_add_u32_e32 v117, s22, v152
	v_ashrrev_i32_e32 v146, 3, v117
	v_mov_b32_e32 v122, 0
	v_mov_b32_e32 v123, 0
	v_mov_b32_e32 v124, 0
	v_mov_b32_e32 v125, 0
	v_mov_b32_e32 v142, 0
	v_mov_b32_e32 v143, 0
	v_mov_b32_e32 v144, 0
	v_mov_b32_e32 v145, 0
	s_and_saveexec_b64 s[22:23], s[14:15]
	s_cbranch_execz .LBB0_779
	v_mov_b64_e32 v[122:123], s[36:37]
	v_mad_i64_i32 v[122:123], s[82:83], v146, s53, v[122:123]
	v_lshl_add_u64 v[122:123], v[184:185], 2, v[122:123]
	v_add_co_u32_e32 v142, vcc, 0xa000, v122
	s_nop 1
	v_addc_co_u32_e32 v143, vcc, 0, v123, vcc
	global_load_dwordx4 v[122:125], v[122:123], off
	s_nop 0
	global_load_dwordx4 v[142:145], v[142:143], off offset:3072
.LBB0_779:
	s_or_b64 exec, exec, s[22:23]
	v_mov_b32_dpp v117, v110 row_shr:1 row_mask:0xf bank_mask:0xf bound_ctrl:1
	v_mov_b32_dpp v148, v110 row_shr:2 row_mask:0xf bank_mask:0xf bound_ctrl:1
	v_mov_b32_dpp v149, v111 row_shr:1 row_mask:0xf bank_mask:0xf bound_ctrl:1
	v_mov_b32_dpp v150, v111 row_shr:2 row_mask:0xf bank_mask:0xf bound_ctrl:1
	v_mov_b32_dpp v151, v112 row_shr:1 row_mask:0xf bank_mask:0xf bound_ctrl:1
	v_mov_b32_dpp v153, v112 row_shr:2 row_mask:0xf bank_mask:0xf bound_ctrl:1
	v_mov_b32_dpp v154, v113 row_shr:1 row_mask:0xf bank_mask:0xf bound_ctrl:1
	v_mov_b32_dpp v155, v113 row_shr:2 row_mask:0xf bank_mask:0xf bound_ctrl:1
	s_and_saveexec_b64 s[22:23], s[12:13]
	s_cbranch_execz .LBB0_781
	v_ashrrev_i32_e32 v147, 31, v146
	v_lshl_add_u64 v[146:147], v[146:147], 1, v[178:179]
	v_mov_b64_e32 v[156:157], s[62:63]
	v_mad_u64_u32 v[156:157], s[82:83], v146, s26, v[156:157]
	v_mad_i32_i24 v157, v147, s26, v157
	v_lshl_add_u64 v[146:147], v[184:185], 2, v[156:157]
	global_store_dwordx4 v[146:147], v[110:113], off

; __device__ __forceinline__ float dpp_shr1(float old, float src) { return __builtin_bit_cast(float, __builtin_amdgcn_update_dpp(__builtin_bit_cast(int, old), __builtin_bit_cast(int, src), 0x111, 0xf, 0xf, false)); }
; __device__ __forceinline__ float dpp_shr2(float old, float src) { return __builtin_bit_cast(float, __builtin_amdgcn_update_dpp(__builtin_bit_cast(int, old), __builtin_bit_cast(int, src), 0x112, 0xf, 0xf, false)); }
; __device__ __forceinline__ float dpp_ror1(float src) { return __builtin_bit_cast(float, __builtin_amdgcn_update_dpp(0, __builtin_bit_cast(int, src), 0x121, 0xf, 0xf, false)); }
; __device__ __forceinline__ float dpp_ror2(float src) { return __builtin_bit_cast(float, __builtin_amdgcn_update_dpp(0, __builtin_bit_cast(int, src), 0x122, 0xf, 0xf, false)); }
;     __device__ __forceinline__ void operator()(const f32x4 (&acc)[2][2][4][2], const Unit& u, int wr, int wc, int fr, int fq) const {
;     ...
;                     const float rsm = RS[16 * m]; const f32x4 g = acc[ai][0][m][n] * rsm, uu = acc[ai][1][m][n] * rsm; f32x4 p1, p2, av;
;                     if (!sample) {
; #pragma unroll
;                         for (int e = 0; e < 4; ++e) { float o1, o2;
;                             if (m == 0) { o1 = bm1[e]; o2 = (fr == 0) ? bm2[e] : bm1[e]; } else { const float gp = acc[ai][0][m > 0 ? m - 1 : 0][n][e] * RS[16 * (m > 0 ? m - 1 : 0)]; o1 = dpp_ror1(gp); o2 = dpp_ror2(gp); }
;                             p1[e] = dpp_shr1(o1, g[e]); p2[e] = dpp_shr2(o2, g[e]); }
.LBB0_782:
	s_and_b64 vcc, exec, s[22:23]
	s_cbranch_vccz .LBB0_784
	v_mov_b32_e32 v117, v239
	v_mov_b32_e32 v146, v179
	v_mov_b32_e32 v122, v179
	v_mov_b32_e32 v142, v179
	v_mov_b32_e32 v123, v179
	s_waitcnt lgkmcnt(0)
	v_mul_f32_e32 v106, v106, v117
	v_mov_b32_e32 v143, v179
	v_mov_b32_e32 v124, v179
	v_mov_b32_dpp v146, v106 row_ror:1 row_mask:0xf bank_mask:0xf
	v_mov_b32_dpp v122, v106 row_ror:2 row_mask:0xf bank_mask:0xf
	v_mul_f32_e32 v106, v107, v117
	v_mov_b32_e32 v144, v179
	v_mov_b32_e32 v125, v179
	v_mov_b32_dpp v142, v106 row_ror:1 row_mask:0xf bank_mask:0xf
	v_mov_b32_dpp v123, v106 row_ror:2 row_mask:0xf bank_mask:0xf
	v_mul_f32_e32 v106, v108, v117
	v_mov_b32_dpp v146, v110 row_shr:1 row_mask:0xf bank_mask:0xf
	v_mov_b32_dpp v122, v110 row_shr:2 row_mask:0xf bank_mask:0xf
	v_mov_b32_dpp v143, v106 row_ror:1 row_mask:0xf bank_mask:0xf
	v_mov_b32_dpp v124, v106 row_ror:2 row_mask:0xf bank_mask:0xf
	v_mul_f32_e32 v106, v109, v117
	v_mov_b32_dpp v142, v111 row_shr:1 row_mask:0xf bank_mask:0xf
	v_mov_b32_dpp v123, v111 row_shr:2 row_mask:0xf bank_mask:0xf
	v_mov_b32_dpp v144, v106 row_ror:1 row_mask:0xf bank_mask:0xf
	v_mov_b32_dpp v125, v106 row_ror:2 row_mask:0xf bank_mask:0xf
	v_mov_b32_dpp v143, v112 row_shr:1 row_mask:0xf bank_mask:0xf
	v_mov_b32_dpp v124, v112 row_shr:2 row_mask:0xf bank_mask:0xf
	v_mov_b32_dpp v144, v113 row_shr:1 row_mask:0xf bank_mask:0xf
	v_mov_b32_dpp v125, v113 row_shr:2 row_mask:0xf bank_mask:0xf

; __device__ __forceinline__ float dpp_shr1(float old, float src) { return __builtin_bit_cast(float, __builtin_amdgcn_update_dpp(__builtin_bit_cast(int, old), __builtin_bit_cast(int, src), 0x111, 0xf, 0xf, false)); }
; __device__ __forceinline__ float dpp_shr2(float old, float src) { return __builtin_bit_cast(float, __builtin_amdgcn_update_dpp(__builtin_bit_cast(int, old), __builtin_bit_cast(int, src), 0x112, 0xf, 0xf, false)); }
; __device__ __forceinline__ float dpp_ror1(float src) { return __builtin_bit_cast(float, __builtin_amdgcn_update_dpp(0, __builtin_bit_cast(int, src), 0x121, 0xf, 0xf, false)); }
;     __device__ __forceinline__ void operator()(const f32x4 (&acc)[2][2][4][2], const Unit& u, int wr, int wc, int fr, int fq) const {
;     ...
;                     const float rsm = RS[16 * m]; const f32x4 g = acc[ai][0][m][n] * rsm, uu = acc[ai][1][m][n] * rsm; f32x4 p1, p2, av;
;                     if (!sample) {
; #pragma unroll
;                         for (int e = 0; e < 4; ++e) { float o1, o2;
;                             if (m == 0) { o1 = bm1[e]; o2 = (fr == 0) ? bm2[e] : bm1[e]; } else { const float gp = acc[ai][0][m > 0 ? m - 1 : 0][n][e] * RS[16 * (m > 0 ? m - 1 : 0)]; o1 = dpp_ror1(gp); o2 = dpp_ror2(gp); }
;                             p1[e] = dpp_shr1(o1, g[e]); p2[e] = dpp_shr2(o2, g[e]); }
;                         if (ai == 0 && wr == 0 && m == 0 && fr < 2 && (u.pm & 7) != 0) {
;                             *(f32x4*)(fix + ((size_t)(72 + u.pm * 2 + fr)) * DFF + j0 + 4 * n) = g; *(f32x4*)(fix + ((size_t)(144 + u.pm * 2 + fr)) * DFF + j0 + 4 * n) = uu; }
;                     } else {
;                         const int t = fr & 7, bs = (r - MP) >> 3; f32x4 s0 = (f32x4){0.f, 0.f, 0.f, 0.f}, s1 = s0;
;                         if (t < 2) { s0 = *(const f32x4*)(st_ffn + ((size_t)bs * 2 + 0) * DFF + j0 + 4 * n); s1 = *(const f32x4*)(st_ffn + ((size_t)bs * 2 + 1) * DFF + j0 + 4 * n); }
; #pragma unroll
;                         for (int e = 0; e < 4; ++e) { const float a1 = dpp_shr1(0.f, g[e]), a2 = dpp_shr2(0.f, g[e]); p1[e] = (t >= 1) ? a1 : s1[e]; p2[e] = (t >= 2) ? a2 : (t == 1 ? s1[e] : s0[e]); }
;                         if (t >= 6) *(f32x4*)(out + O_SFFN + ((size_t)bs * 2 + (t - 6)) * DFF + j0 + 4 * n) = g;
.LBB0_786:
	v_lshl_add_u32 v150, v186, 2, s29
	v_mov_b32_e32 v112, v241
	v_add_u32_e32 v151, 0x80, v217
	s_and_b64 vcc, exec, s[16:17]
	s_mov_b64 s[80:81], -1
	s_waitcnt lgkmcnt(0)
	v_pk_mul_f32 v[106:107], v[96:97], v[112:113] op_sel_hi:[1,0]
	v_pk_mul_f32 v[104:105], v[94:95], v[112:113] op_sel_hi:[1,0]
	s_cbranch_vccnz .LBB0_792
	s_add_i32 s65, s74, 0xffffe000
	v_add_u32_e32 v113, s65, v151
	v_ashrrev_i32_e32 v116, 3, v113
	v_mov_b32_e32 v142, 0
	v_mov_b32_e32 v143, 0
	v_mov_b32_e32 v144, 0
	v_mov_b32_e32 v145, 0
	v_mov_b32_e32 v146, 0
	v_mov_b32_e32 v147, 0
	v_mov_b32_e32 v148, 0
	v_mov_b32_e32 v149, 0
	s_and_saveexec_b64 s[80:81], s[14:15]
	s_cbranch_execz .LBB0_789
	v_mov_b64_e32 v[142:143], s[36:37]
	v_mad_i64_i32 v[142:143], s[82:83], v116, s53, v[142:143]
	v_lshl_add_u64 v[142:143], v[184:185], 2, v[142:143]
	v_add_co_u32_e32 v146, vcc, 0xa000, v142
	s_nop 1
	v_addc_co_u32_e32 v147, vcc, 0, v143, vcc
	global_load_dwordx4 v[142:145], v[142:143], off
	s_nop 0
	global_load_dwordx4 v[146:149], v[146:147], off offset:3072
.LBB0_789:
	s_or_b64 exec, exec, s[80:81]
	v_mov_b32_dpp v113, v104 row_shr:1 row_mask:0xf bank_mask:0xf bound_ctrl:1
	v_mov_b32_dpp v155, v104 row_shr:2 row_mask:0xf bank_mask:0xf bound_ctrl:1
	v_mov_b32_dpp v156, v105 row_shr:1 row_mask:0xf bank_mask:0xf bound_ctrl:1
	v_mov_b32_dpp v157, v105 row_shr:2 row_mask:0xf bank_mask:0xf bound_ctrl:1
	v_mov_b32_dpp v159, v106 row_shr:1 row_mask:0xf bank_mask:0xf bound_ctrl:1
	v_mov_b32_dpp v160, v106 row_shr:2 row_mask:0xf bank_mask:0xf bound_ctrl:1
	v_mov_b32_dpp v161, v107 row_shr:1 row_mask:0xf bank_mask:0xf bound_ctrl:1
	v_mov_b32_dpp v162, v107 row_shr:2 row_mask:0xf bank_mask:0xf bound_ctrl:1
	s_and_saveexec_b64 s[80:81], s[12:13]
	s_cbranch_execz .LBB0_791
	v_ashrrev_i32_e32 v117, 31, v116
	v_lshl_add_u64 v[116:117], v[116:117], 1, v[178:179]
	v_mov_b64_e32 v[168:169], s[62:63]
	v_mad_u64_u32 v[168:169], s[82:83], v116, s26, v[168:169]
	v_mad_i32_i24 v169, v117, s26, v169
	v_lshl_add_u64 v[116:117], v[184:185], 2, v[168:169]
	global_store_dwordx4 v[116:117], v[104:107], off

; __device__ __forceinline__ unsigned cvt_pk_bf16(float lo, float hi) { unsigned r; asm volatile("v_cvt_pk_bf16_f32 %0, %1, %2" : "=v"(r) : "v"(lo), "v"(hi)); return r; }
;     __device__ __forceinline__ void operator()(const f32x4 (&acc)[2][2][4][2], const Unit& u, int wr, int wc, int fr, int fq) const {
;     ...
;                     const float rsm = RS[16 * m]; const f32x4 g = acc[ai][0][m][n] * rsm, uu = acc[ai][1][m][n] * rsm; f32x4 p1, p2, av;
;                     if (!sample) {
; #pragma unroll
;                         for (int e = 0; e < 4; ++e) { float o1, o2;
;                             if (m == 0) { o1 = bm1[e]; o2 = (fr == 0) ? bm2[e] : bm1[e]; } else { const float gp = acc[ai][0][m > 0 ? m - 1 : 0][n][e] * RS[16 * (m > 0 ? m - 1 : 0)]; o1 = dpp_ror1(gp); o2 = dpp_ror2(gp); }
;                             p1[e] = dpp_shr1(o1, g[e]); p2[e] = dpp_shr2(o2, g[e]); }
;                         if (ai == 0 && wr == 0 && m == 0 && fr < 2 && (u.pm & 7) != 0) {
;                             *(f32x4*)(fix + ((size_t)(72 + u.pm * 2 + fr)) * DFF + j0 + 4 * n) = g; *(f32x4*)(fix + ((size_t)(144 + u.pm * 2 + fr)) * DFF + j0 + 4 * n) = uu; }
;                     } else {
;                         const int t = fr & 7, bs = (r - MP) >> 3; f32x4 s0 = (f32x4){0.f, 0.f, 0.f, 0.f}, s1 = s0;
;                         if (t < 2) { s0 = *(const f32x4*)(st_ffn + ((size_t)bs * 2 + 0) * DFF + j0 + 4 * n); s1 = *(const f32x4*)(st_ffn + ((size_t)bs * 2 + 1) * DFF + j0 + 4 * n); }
; #pragma unroll
;                         for (int e = 0; e < 4; ++e) { const float a1 = dpp_shr1(0.f, g[e]), a2 = dpp_shr2(0.f, g[e]); p1[e] = (t >= 1) ? a1 : s1[e]; p2[e] = (t >= 2) ? a2 : (t == 1 ? s1[e] : s0[e]); }
;                         if (t >= 6) *(f32x4*)(out + O_SFFN + ((size_t)bs * 2 + (t - 6)) * DFF + j0 + 4 * n) = g;
;                     }
;                     const f32x4 gc = bb + w0 * p2 + w1 * p1 + w2 * g;
; #pragma unroll
;                     for (int e = 0; e < 4; ++e) av[e] = silu_e(gc[e]) * uu[e];
;                     if (n == 0) { keep[ai][m].x = cvt_pk_bf16(av[0], av[1]); keep[ai][m].y = cvt_pk_bf16(av[2], av[3]); }
;                     else { u32x4e w; w.x = keep[ai][m].x; w.y = keep[ai][m].y; w.z = cvt_pk_bf16(av[0], av[1]); w.w = cvt_pk_bf16(av[2], av[3]); *(u32x4e*)(ACT + act_off(r, j0)) = w; }
.LBB0_794:
	v_fma_f32 v110, v141, v144, v129
	v_fmac_f32_e32 v110, v137, v147
	v_fmac_f32_e32 v110, v133, v107
	v_mul_f32_e32 v107, 0xbfb8aa3b, v110
	v_exp_f32_e32 v107, v107
	v_mov_b32_e32 v108, v112
	v_mov_b32_e32 v109, v112
	v_pk_mul_f32 v[100:101], v[100:101], v[108:109]
	v_add_f32_e32 v107, 1.0, v107
	v_rcp_f32_e32 v107, v107
	v_fma_f32 v108, v140, v143, v128
	v_fma_f32 v109, v138, v116, v126
	v_fmac_f32_e32 v108, v136, v146
	v_mul_f32_e32 v107, v110, v107
	v_mul_f32_e32 v101, v101, v107
	v_fma_f32 v107, v139, v117, v127
	v_fmac_f32_e32 v107, v135, v142
	v_fmac_f32_e32 v109, v134, v154
	v_fmac_f32_e32 v108, v132, v106
	v_fmac_f32_e32 v107, v131, v105
	v_fmac_f32_e32 v109, v130, v104
	v_mul_f32_e32 v106, 0xbfb8aa3b, v108
	v_mul_f32_e32 v105, 0xbfb8aa3b, v107
	v_mul_f32_e32 v104, 0xbfb8aa3b, v109
	v_exp_f32_e32 v106, v106
	v_exp_f32_e32 v105, v105
	v_exp_f32_e32 v104, v104
	v_mov_b32_e32 v113, v112
	v_add_f32_e32 v106, 1.0, v106
	v_add_f32_e32 v105, 1.0, v105
	v_add_f32_e32 v104, 1.0, v104
	v_rcp_f32_e32 v106, v106
	v_rcp_f32_e32 v105, v105
	v_rcp_f32_e32 v104, v104
	v_pk_mul_f32 v[98:99], v[98:99], v[112:113]
	v_mul_f32_e32 v106, v108, v106
	v_mul_f32_e32 v105, v107, v105
	v_mul_f32_e32 v104, v109, v104
	v_mul_f32_e32 v100, v100, v106
	v_mul_f32_e32 v99, v99, v105
	v_mul_f32_e32 v98, v98, v104
	v_cvt_pk_bf16_f32 v98, v98, v99
	v_cvt_pk_bf16_f32 v99, v100, v101
	v_mov_b32_e32 v100, v242
	v_add_u32_e32 v142, 0x90, v217
	s_and_b64 vcc, exec, s[16:17]
	s_mov_b64 s[80:81], -1
	s_waitcnt lgkmcnt(0)
	v_pk_mul_f32 v[106:107], v[88:89], v[100:101] op_sel_hi:[1,0]
	v_pk_mul_f32 v[104:105], v[86:87], v[100:101] op_sel_hi:[1,0]
	s_cbranch_vccnz .LBB0_800
	s_add_i32 s65, s74, 0xffffe000
	v_add_u32_e32 v101, s65, v142
	v_ashrrev_i32_e32 v112, 3, v101
	v_mov_b32_e32 v108, 0
	v_mov_b32_e32 v109, 0
	v_mov_b32_e32 v110, 0
	v_mov_b32_e32 v111, 0
	v_mov_b32_e32 v122, 0
	v_mov_b32_e32 v123, 0
	v_mov_b32_e32 v124, 0
	v_mov_b32_e32 v125, 0
	s_and_saveexec_b64 s[80:81], s[14:15]
	s_cbranch_execz .LBB0_797
	v_mov_b64_e32 v[108:109], s[36:37]
	v_mad_i64_i32 v[108:109], s[82:83], v112, s53, v[108:109]
	v_lshl_add_u64 v[108:109], v[184:185], 2, v[108:109]
	v_add_co_u32_e32 v116, vcc, 0xa000, v108
	s_nop 1
	v_addc_co_u32_e32 v117, vcc, 0, v109, vcc
	global_load_dwordx4 v[108:111], v[108:109], off
	s_nop 0
	global_load_dwordx4 v[122:125], v[116:117], off offset:3072
.LBB0_797:
	s_or_b64 exec, exec, s[80:81]
	v_mov_b32_dpp v101, v104 row_shr:1 row_mask:0xf bank_mask:0xf bound_ctrl:1
	v_mov_b32_dpp v116, v104 row_shr:2 row_mask:0xf bank_mask:0xf bound_ctrl:1
	v_mov_b32_dpp v117, v105 row_shr:1 row_mask:0xf bank_mask:0xf bound_ctrl:1
	v_mov_b32_dpp v143, v105 row_shr:2 row_mask:0xf bank_mask:0xf bound_ctrl:1
	v_mov_b32_dpp v144, v106 row_shr:1 row_mask:0xf bank_mask:0xf bound_ctrl:1
	v_mov_b32_dpp v145, v106 row_shr:2 row_mask:0xf bank_mask:0xf bound_ctrl:1
	v_mov_b32_dpp v146, v107 row_shr:1 row_mask:0xf bank_mask:0xf bound_ctrl:1
	v_mov_b32_dpp v147, v107 row_shr:2 row_mask:0xf bank_mask:0xf bound_ctrl:1
	s_and_saveexec_b64 s[80:81], s[12:13]
	s_cbranch_execz .LBB0_799
	v_ashrrev_i32_e32 v113, 31, v112
	v_lshl_add_u64 v[112:113], v[112:113], 1, v[178:179]
	v_mov_b64_e32 v[148:149], s[62:63]
	v_mad_u64_u32 v[148:149], s[82:83], v112, s26, v[148:149]
	v_mad_i32_i24 v149, v113, s26, v149
	v_lshl_add_u64 v[112:113], v[184:185], 2, v[148:149]
	global_store_dwordx4 v[112:113], v[104:107], off

; __device__ __forceinline__ unsigned cvt_pk_bf16(float lo, float hi) { unsigned r; asm volatile("v_cvt_pk_bf16_f32 %0, %1, %2" : "=v"(r) : "v"(lo), "v"(hi)); return r; }
;     __device__ __forceinline__ void operator()(const f32x4 (&acc)[2][2][4][2], const Unit& u, int wr, int wc, int fr, int fq) const {
;     ...
;                     const float rsm = RS[16 * m]; const f32x4 g = acc[ai][0][m][n] * rsm, uu = acc[ai][1][m][n] * rsm; f32x4 p1, p2, av;
;                     if (!sample) {
; #pragma unroll
;                         for (int e = 0; e < 4; ++e) { float o1, o2;
;                             if (m == 0) { o1 = bm1[e]; o2 = (fr == 0) ? bm2[e] : bm1[e]; } else { const float gp = acc[ai][0][m > 0 ? m - 1 : 0][n][e] * RS[16 * (m > 0 ? m - 1 : 0)]; o1 = dpp_ror1(gp); o2 = dpp_ror2(gp); }
;                             p1[e] = dpp_shr1(o1, g[e]); p2[e] = dpp_shr2(o2, g[e]); }
;                         if (ai == 0 && wr == 0 && m == 0 && fr < 2 && (u.pm & 7) != 0) {
;                             *(f32x4*)(fix + ((size_t)(72 + u.pm * 2 + fr)) * DFF + j0 + 4 * n) = g; *(f32x4*)(fix + ((size_t)(144 + u.pm * 2 + fr)) * DFF + j0 + 4 * n) = uu; }
;                     } else {
;                         const int t = fr & 7, bs = (r - MP) >> 3; f32x4 s0 = (f32x4){0.f, 0.f, 0.f, 0.f}, s1 = s0;
;                         if (t < 2) { s0 = *(const f32x4*)(st_ffn + ((size_t)bs * 2 + 0) * DFF + j0 + 4 * n); s1 = *(const f32x4*)(st_ffn + ((size_t)bs * 2 + 1) * DFF + j0 + 4 * n); }
; #pragma unroll
;                         for (int e = 0; e < 4; ++e) { const float a1 = dpp_shr1(0.f, g[e]), a2 = dpp_shr2(0.f, g[e]); p1[e] = (t >= 1) ? a1 : s1[e]; p2[e] = (t >= 2) ? a2 : (t == 1 ? s1[e] : s0[e]); }
;                         if (t >= 6) *(f32x4*)(out + O_SFFN + ((size_t)bs * 2 + (t - 6)) * DFF + j0 + 4 * n) = g;
;                     }
;                     const f32x4 gc = bb + w0 * p2 + w1 * p1 + w2 * g;
; #pragma unroll
;                     for (int e = 0; e < 4; ++e) av[e] = silu_e(gc[e]) * uu[e];
;                     if (n == 0) { keep[ai][m].x = cvt_pk_bf16(av[0], av[1]); keep[ai][m].y = cvt_pk_bf16(av[2], av[3]); }
;                     else { u32x4e w; w.x = keep[ai][m].x; w.y = keep[ai][m].y; w.z = cvt_pk_bf16(av[0], av[1]); w.w = cvt_pk_bf16(av[2], av[3]); *(u32x4e*)(ACT + act_off(r, j0)) = w; }
.LBB0_800:
	s_and_b64 vcc, exec, s[80:81]
	s_cbranch_vccz .LBB0_802
	v_mov_b32_e32 v101, v241
	v_mov_b32_e32 v112, v179
	v_mov_b32_e32 v108, v179
	v_mov_b32_e32 v113, v179
	v_mov_b32_e32 v109, v179
	s_waitcnt lgkmcnt(0)
	v_mul_f32_e32 v94, v94, v101
	v_mov_b32_e32 v116, v179
	v_mov_b32_e32 v110, v179
	v_mov_b32_dpp v112, v94 row_ror:1 row_mask:0xf bank_mask:0xf
	v_mov_b32_dpp v108, v94 row_ror:2 row_mask:0xf bank_mask:0xf
	v_mul_f32_e32 v94, v95, v101
	v_mov_b32_e32 v117, v179
	v_mov_b32_e32 v111, v179
	v_mov_b32_dpp v113, v94 row_ror:1 row_mask:0xf bank_mask:0xf
	v_mov_b32_dpp v109, v94 row_ror:2 row_mask:0xf bank_mask:0xf
	v_mul_f32_e32 v94, v96, v101
	v_mov_b32_dpp v112, v104 row_shr:1 row_mask:0xf bank_mask:0xf
	v_mov_b32_dpp v108, v104 row_shr:2 row_mask:0xf bank_mask:0xf
	v_mov_b32_dpp v116, v94 row_ror:1 row_mask:0xf bank_mask:0xf
	v_mov_b32_dpp v110, v94 row_ror:2 row_mask:0xf bank_mask:0xf
	v_mul_f32_e32 v94, v97, v101
	v_mov_b32_dpp v113, v105 row_shr:1 row_mask:0xf bank_mask:0xf
	v_mov_b32_dpp v109, v105 row_shr:2 row_mask:0xf bank_mask:0xf
	v_mov_b32_dpp v117, v94 row_ror:1 row_mask:0xf bank_mask:0xf
	v_mov_b32_dpp v111, v94 row_ror:2 row_mask:0xf bank_mask:0xf
	v_mov_b32_dpp v116, v106 row_shr:1 row_mask:0xf bank_mask:0xf
	v_mov_b32_dpp v110, v106 row_shr:2 row_mask:0xf bank_mask:0xf
	v_mov_b32_dpp v117, v107 row_shr:1 row_mask:0xf bank_mask:0xf
	v_mov_b32_dpp v111, v107 row_shr:2 row_mask:0xf bank_mask:0xf
.LBB0_802:
	v_fma_f32 v96, v141, v111, v129
	v_fmac_f32_e32 v96, v137, v117
	v_fmac_f32_e32 v96, v133, v107
	v_mul_f32_e32 v94, 0xbfb8aa3b, v96
	v_exp_f32_e32 v97, v94
	v_mov_b32_e32 v94, v100
	v_mov_b32_e32 v95, v100
	v_pk_mul_f32 v[92:93], v[92:93], v[94:95]
	v_add_f32_e32 v94, 1.0, v97
	v_fma_f32 v95, v140, v110, v128
	v_rcp_f32_e32 v94, v94
	v_fmac_f32_e32 v95, v136, v116
	v_fmac_f32_e32 v95, v132, v106
	v_mul_f32_e32 v97, 0xbfb8aa3b, v95
	v_exp_f32_e32 v97, v97
	v_mov_b32_e32 v101, v100
	v_mul_f32_e32 v94, v96, v94
	v_fma_f32 v96, v139, v109, v127
	v_pk_mul_f32 v[90:91], v[90:91], v[100:101]
	v_fmac_f32_e32 v96, v135, v113
	v_fma_f32 v100, v138, v108, v126
	v_fmac_f32_e32 v96, v131, v105
	v_fmac_f32_e32 v100, v134, v112
	v_mul_f32_e32 v93, v93, v94
	v_add_f32_e32 v94, 1.0, v97
	v_mul_f32_e32 v97, 0xbfb8aa3b, v96
	v_fmac_f32_e32 v100, v130, v104
	v_rcp_f32_e32 v94, v94
	v_exp_f32_e32 v97, v97
	v_mul_f32_e32 v101, 0xbfb8aa3b, v100
	v_exp_f32_e32 v101, v101
	v_mul_f32_e32 v94, v95, v94
	v_add_f32_e32 v95, 1.0, v97
	v_rcp_f32_e32 v95, v95
	v_add_f32_e32 v97, 1.0, v101
	v_rcp_f32_e32 v97, v97
	v_mul_f32_e32 v92, v92, v94
	v_mul_f32_e32 v94, v96, v95
	v_mul_f32_e32 v91, v91, v94
	v_mul_f32_e32 v94, v100, v97
	v_mul_f32_e32 v90, v90, v94
	v_cvt_pk_bf16_f32 v90, v90, v91
	v_cvt_pk_bf16_f32 v91, v92, v93
	v_mov_b32_e32 v96, v243
	v_add_u32_e32 v113, 0xa0, v217
	s_and_b64 vcc, exec, s[16:17]
	s_mov_b64 s[80:81], -1
	s_waitcnt lgkmcnt(0)
	v_pk_mul_f32 v[94:95], v[76:77], v[96:97] op_sel_hi:[1,0]
	v_pk_mul_f32 v[92:93], v[74:75], v[96:97] op_sel_hi:[1,0]
	s_cbranch_vccnz .LBB0_808
	s_add_i32 s65, s74, 0xffffe000
	v_add_u32_e32 v97, s65, v113
	v_ashrrev_i32_e32 v100, 3, v97
	v_mov_b32_e32 v104, 0
	v_mov_b32_e32 v105, 0
	v_mov_b32_e32 v106, 0
	v_mov_b32_e32 v107, 0
	v_mov_b32_e32 v108, 0
	v_mov_b32_e32 v109, 0
	v_mov_b32_e32 v110, 0
	v_mov_b32_e32 v111, 0
	s_and_saveexec_b64 s[80:81], s[14:15]
	s_cbranch_execz .LBB0_805
	v_mov_b64_e32 v[104:105], s[36:37]
	v_mad_i64_i32 v[104:105], s[82:83], v100, s53, v[104:105]
	v_lshl_add_u64 v[104:105], v[184:185], 2, v[104:105]
	v_add_co_u32_e32 v108, vcc, 0xa000, v104
	s_nop 1
	v_addc_co_u32_e32 v109, vcc, 0, v105, vcc
	global_load_dwordx4 v[104:107], v[104:105], off
	s_nop 0
	global_load_dwordx4 v[108:111], v[108:109], off offset:3072
.LBB0_805:
	s_or_b64 exec, exec, s[80:81]
	v_mov_b32_dpp v97, v92 row_shr:1 row_mask:0xf bank_mask:0xf bound_ctrl:1
	v_mov_b32_dpp v112, v92 row_shr:2 row_mask:0xf bank_mask:0xf bound_ctrl:1
	v_mov_b32_dpp v116, v93 row_shr:1 row_mask:0xf bank_mask:0xf bound_ctrl:1
	v_mov_b32_dpp v117, v93 row_shr:2 row_mask:0xf bank_mask:0xf bound_ctrl:1
	v_mov_b32_dpp v122, v94 row_shr:1 row_mask:0xf bank_mask:0xf bound_ctrl:1
	v_mov_b32_dpp v123, v94 row_shr:2 row_mask:0xf bank_mask:0xf bound_ctrl:1
	v_mov_b32_dpp v124, v95 row_shr:1 row_mask:0xf bank_mask:0xf bound_ctrl:1
	v_mov_b32_dpp v125, v95 row_shr:2 row_mask:0xf bank_mask:0xf bound_ctrl:1
	s_and_saveexec_b64 s[80:81], s[12:13]
	s_cbranch_execz .LBB0_807
	v_ashrrev_i32_e32 v101, 31, v100
	v_lshl_add_u64 v[100:101], v[100:101], 1, v[178:179]
	v_mov_b64_e32 v[144:145], s[62:63]
	v_mad_u64_u32 v[144:145], s[82:83], v100, s26, v[144:145]
	v_mad_i32_i24 v145, v101, s26, v145
	v_lshl_add_u64 v[100:101], v[184:185], 2, v[144:145]
	global_store_dwordx4 v[100:101], v[92:95], off

; __device__ __forceinline__ unsigned cvt_pk_bf16(float lo, float hi) { unsigned r; asm volatile("v_cvt_pk_bf16_f32 %0, %1, %2" : "=v"(r) : "v"(lo), "v"(hi)); return r; }
;     __device__ __forceinline__ void operator()(const f32x4 (&acc)[2][2][4][2], const Unit& u, int wr, int wc, int fr, int fq) const {
;     ...
;                     const float rsm = RS[16 * m]; const f32x4 g = acc[ai][0][m][n] * rsm, uu = acc[ai][1][m][n] * rsm; f32x4 p1, p2, av;
;                     if (!sample) {
; #pragma unroll
;                         for (int e = 0; e < 4; ++e) { float o1, o2;
;                             if (m == 0) { o1 = bm1[e]; o2 = (fr == 0) ? bm2[e] : bm1[e]; } else { const float gp = acc[ai][0][m > 0 ? m - 1 : 0][n][e] * RS[16 * (m > 0 ? m - 1 : 0)]; o1 = dpp_ror1(gp); o2 = dpp_ror2(gp); }
;                             p1[e] = dpp_shr1(o1, g[e]); p2[e] = dpp_shr2(o2, g[e]); }
;                         if (ai == 0 && wr == 0 && m == 0 && fr < 2 && (u.pm & 7) != 0) {
;                             *(f32x4*)(fix + ((size_t)(72 + u.pm * 2 + fr)) * DFF + j0 + 4 * n) = g; *(f32x4*)(fix + ((size_t)(144 + u.pm * 2 + fr)) * DFF + j0 + 4 * n) = uu; }
;                     } else {
;                         const int t = fr & 7, bs = (r - MP) >> 3; f32x4 s0 = (f32x4){0.f, 0.f, 0.f, 0.f}, s1 = s0;
;                         if (t < 2) { s0 = *(const f32x4*)(st_ffn + ((size_t)bs * 2 + 0) * DFF + j0 + 4 * n); s1 = *(const f32x4*)(st_ffn + ((size_t)bs * 2 + 1) * DFF + j0 + 4 * n); }
; #pragma unroll
;                         for (int e = 0; e < 4; ++e) { const float a1 = dpp_shr1(0.f, g[e]), a2 = dpp_shr2(0.f, g[e]); p1[e] = (t >= 1) ? a1 : s1[e]; p2[e] = (t >= 2) ? a2 : (t == 1 ? s1[e] : s0[e]); }
;                         if (t >= 6) *(f32x4*)(out + O_SFFN + ((size_t)bs * 2 + (t - 6)) * DFF + j0 + 4 * n) = g;
;                     }
;                     const f32x4 gc = bb + w0 * p2 + w1 * p1 + w2 * g;
; #pragma unroll
;                     for (int e = 0; e < 4; ++e) av[e] = silu_e(gc[e]) * uu[e];
;                     if (n == 0) { keep[ai][m].x = cvt_pk_bf16(av[0], av[1]); keep[ai][m].y = cvt_pk_bf16(av[2], av[3]); }
;                     else { u32x4e w; w.x = keep[ai][m].x; w.y = keep[ai][m].y; w.z = cvt_pk_bf16(av[0], av[1]); w.w = cvt_pk_bf16(av[2], av[3]); *(u32x4e*)(ACT + act_off(r, j0)) = w; }
.LBB0_808:
	s_and_b64 vcc, exec, s[80:81]
	s_cbranch_vccz .LBB0_810
	v_mov_b32_e32 v97, v242
	v_mov_b32_e32 v100, v179
	v_mov_b32_e32 v101, v179
	v_mov_b32_e32 v104, v179
	v_mov_b32_e32 v105, v179
	s_waitcnt lgkmcnt(0)
	v_mul_f32_e32 v86, v86, v97
	v_mov_b32_e32 v108, v179
	v_mov_b32_e32 v106, v179
	v_mov_b32_dpp v100, v86 row_ror:1 row_mask:0xf bank_mask:0xf
	v_mov_b32_dpp v101, v86 row_ror:2 row_mask:0xf bank_mask:0xf
	v_mul_f32_e32 v86, v87, v97
	v_mov_b32_e32 v109, v179
	v_mov_b32_e32 v107, v179
	v_mov_b32_dpp v104, v86 row_ror:1 row_mask:0xf bank_mask:0xf
	v_mov_b32_dpp v105, v86 row_ror:2 row_mask:0xf bank_mask:0xf
	v_mul_f32_e32 v86, v88, v97
	v_mov_b32_dpp v100, v92 row_shr:1 row_mask:0xf bank_mask:0xf
	v_mov_b32_dpp v101, v92 row_shr:2 row_mask:0xf bank_mask:0xf
	v_mov_b32_dpp v108, v86 row_ror:1 row_mask:0xf bank_mask:0xf
	v_mov_b32_dpp v106, v86 row_ror:2 row_mask:0xf bank_mask:0xf
	v_mul_f32_e32 v86, v89, v97
	v_mov_b32_dpp v104, v93 row_shr:1 row_mask:0xf bank_mask:0xf
	v_mov_b32_dpp v105, v93 row_shr:2 row_mask:0xf bank_mask:0xf
	v_mov_b32_dpp v109, v86 row_ror:1 row_mask:0xf bank_mask:0xf
	v_mov_b32_dpp v107, v86 row_ror:2 row_mask:0xf bank_mask:0xf
	v_mov_b32_dpp v108, v94 row_shr:1 row_mask:0xf bank_mask:0xf
	v_mov_b32_dpp v106, v94 row_shr:2 row_mask:0xf bank_mask:0xf
	v_mov_b32_dpp v109, v95 row_shr:1 row_mask:0xf bank_mask:0xf
	v_mov_b32_dpp v107, v95 row_shr:2 row_mask:0xf bank_mask:0xf
.LBB0_810:
	v_fma_f32 v88, v141, v107, v129
	v_fmac_f32_e32 v88, v137, v109
	v_fmac_f32_e32 v88, v133, v95
	v_mul_f32_e32 v86, 0xbfb8aa3b, v88
	v_exp_f32_e32 v89, v86
	v_mov_b32_e32 v86, v96
	v_mov_b32_e32 v87, v96
	v_pk_mul_f32 v[84:85], v[84:85], v[86:87]
	v_add_f32_e32 v86, 1.0, v89
	v_rcp_f32_e32 v86, v86
	v_fma_f32 v87, v140, v106, v128
	v_fmac_f32_e32 v87, v136, v108
	v_fmac_f32_e32 v87, v132, v94
	v_mul_f32_e32 v89, 0xbfb8aa3b, v87
	v_exp_f32_e32 v89, v89
	v_mul_f32_e32 v86, v88, v86
	v_fma_f32 v88, v139, v105, v127
	v_fmac_f32_e32 v88, v135, v104
	v_fmac_f32_e32 v88, v131, v93
	v_fma_f32 v93, v138, v101, v126
	v_fmac_f32_e32 v93, v134, v100
	v_mul_f32_e32 v85, v85, v86
	v_add_f32_e32 v86, 1.0, v89
	v_mul_f32_e32 v89, 0xbfb8aa3b, v88
	v_fmac_f32_e32 v93, v130, v92
	v_rcp_f32_e32 v86, v86
	v_exp_f32_e32 v89, v89
	v_mul_f32_e32 v92, 0xbfb8aa3b, v93
	v_exp_f32_e32 v92, v92
	v_mul_f32_e32 v86, v87, v86
	v_add_f32_e32 v87, 1.0, v89
	v_rcp_f32_e32 v87, v87
	v_add_f32_e32 v89, 1.0, v92
	v_rcp_f32_e32 v89, v89
	v_mov_b32_e32 v97, v96
	v_pk_mul_f32 v[82:83], v[82:83], v[96:97]
	v_mul_f32_e32 v84, v84, v86
	v_mul_f32_e32 v86, v88, v87
	v_mul_f32_e32 v83, v83, v86
	v_mul_f32_e32 v86, v93, v89
	v_mul_f32_e32 v82, v82, v86
	v_cvt_pk_bf16_f32 v82, v82, v83
	v_cvt_pk_bf16_f32 v83, v84, v85
	v_mov_b32_e32 v88, v244
	v_add_u32_e32 v112, 0xb0, v217
	s_and_b64 vcc, exec, s[16:17]
	s_mov_b64 s[80:81], -1
	s_waitcnt lgkmcnt(0)
	v_pk_mul_f32 v[80:81], v[80:81], v[88:89] op_sel_hi:[1,0]
	v_pk_mul_f32 v[78:79], v[78:79], v[88:89] op_sel_hi:[1,0]
	s_cbranch_vccnz .LBB0_816
	s_add_i32 s65, s74, 0xffffe000
	v_add_u32_e32 v84, s65, v112
	v_ashrrev_i32_e32 v96, 3, v84
	v_mov_b32_e32 v84, 0
	v_mov_b32_e32 v85, 0
	v_mov_b32_e32 v86, 0
	v_mov_b32_e32 v87, 0
	v_mov_b32_e32 v92, 0
	v_mov_b32_e32 v93, 0
	v_mov_b32_e32 v94, 0
	v_mov_b32_e32 v95, 0
	s_and_saveexec_b64 s[80:81], s[14:15]
	s_cbranch_execz .LBB0_813
	v_mov_b64_e32 v[84:85], s[36:37]
	v_mad_i64_i32 v[84:85], s[82:83], v96, s53, v[84:85]
	v_lshl_add_u64 v[84:85], v[184:185], 2, v[84:85]
	v_add_co_u32_e32 v92, vcc, 0xa000, v84
	s_nop 1
	v_addc_co_u32_e32 v93, vcc, 0, v85, vcc
	global_load_dwordx4 v[84:87], v[84:85], off
	s_nop 0
	global_load_dwordx4 v[92:95], v[92:93], off offset:3072
.LBB0_813:
	s_or_b64 exec, exec, s[80:81]
	v_mov_b32_dpp v89, v78 row_shr:1 row_mask:0xf bank_mask:0xf bound_ctrl:1
	v_mov_b32_dpp v100, v78 row_shr:2 row_mask:0xf bank_mask:0xf bound_ctrl:1
	v_mov_b32_dpp v101, v79 row_shr:1 row_mask:0xf bank_mask:0xf bound_ctrl:1
	v_mov_b32_dpp v104, v79 row_shr:2 row_mask:0xf bank_mask:0xf bound_ctrl:1
	v_mov_b32_dpp v105, v80 row_shr:1 row_mask:0xf bank_mask:0xf bound_ctrl:1
	v_mov_b32_dpp v106, v80 row_shr:2 row_mask:0xf bank_mask:0xf bound_ctrl:1
	v_mov_b32_dpp v107, v81 row_shr:1 row_mask:0xf bank_mask:0xf bound_ctrl:1
	v_mov_b32_dpp v108, v81 row_shr:2 row_mask:0xf bank_mask:0xf bound_ctrl:1
	s_and_saveexec_b64 s[80:81], s[12:13]
	s_cbranch_execz .LBB0_815
	v_ashrrev_i32_e32 v97, 31, v96
	v_lshl_add_u64 v[96:97], v[96:97], 1, v[178:179]
	v_mov_b64_e32 v[110:111], s[62:63]
	v_mad_u64_u32 v[110:111], s[82:83], v96, s26, v[110:111]
	v_mad_i32_i24 v111, v97, s26, v111
	v_lshl_add_u64 v[96:97], v[184:185], 2, v[110:111]
	global_store_dwordx4 v[96:97], v[78:81], off

; __device__ __forceinline__ float dpp_shr1(float old, float src) { return __builtin_bit_cast(float, __builtin_amdgcn_update_dpp(__builtin_bit_cast(int, old), __builtin_bit_cast(int, src), 0x111, 0xf, 0xf, false)); }
; __device__ __forceinline__ float dpp_shr2(float old, float src) { return __builtin_bit_cast(float, __builtin_amdgcn_update_dpp(__builtin_bit_cast(int, old), __builtin_bit_cast(int, src), 0x112, 0xf, 0xf, false)); }
; __device__ __forceinline__ float dpp_ror1(float src) { return __builtin_bit_cast(float, __builtin_amdgcn_update_dpp(0, __builtin_bit_cast(int, src), 0x121, 0xf, 0xf, false)); }
; __device__ __forceinline__ float dpp_ror2(float src) { return __builtin_bit_cast(float, __builtin_amdgcn_update_dpp(0, __builtin_bit_cast(int, src), 0x122, 0xf, 0xf, false)); }
;     __device__ __forceinline__ void operator()(const f32x4 (&acc)[2][2][4][2], const Unit& u, int wr, int wc, int fr, int fq) const {
;     ...
;                     const float rsm = RS[16 * m]; const f32x4 g = acc[ai][0][m][n] * rsm, uu = acc[ai][1][m][n] * rsm; f32x4 p1, p2, av;
;                     if (!sample) {
; #pragma unroll
;                         for (int e = 0; e < 4; ++e) { float o1, o2;
;                             if (m == 0) { o1 = bm1[e]; o2 = (fr == 0) ? bm2[e] : bm1[e]; } else { const float gp = acc[ai][0][m > 0 ? m - 1 : 0][n][e] * RS[16 * (m > 0 ? m - 1 : 0)]; o1 = dpp_ror1(gp); o2 = dpp_ror2(gp); }
;                             p1[e] = dpp_shr1(o1, g[e]); p2[e] = dpp_shr2(o2, g[e]); }
.LBB0_816:
	s_and_b64 vcc, exec, s[80:81]
	s_cbranch_vccz .LBB0_818
	v_mov_b32_e32 v87, v243
	v_mov_b32_e32 v96, v179
	v_mov_b32_e32 v84, v179
	v_mov_b32_e32 v92, v179
	v_mov_b32_e32 v85, v179
	s_waitcnt lgkmcnt(0)
	v_mul_f32_e32 v74, v74, v87
	v_mov_b32_e32 v93, v179
	v_mov_b32_e32 v86, v179
	v_mov_b32_dpp v96, v74 row_ror:1 row_mask:0xf bank_mask:0xf
	v_mov_b32_dpp v84, v74 row_ror:2 row_mask:0xf bank_mask:0xf
	v_mul_f32_e32 v74, v75, v87
	v_mov_b32_e32 v94, v179
	v_mov_b32_dpp v96, v78 row_shr:1 row_mask:0xf bank_mask:0xf
	v_mov_b32_dpp v92, v74 row_ror:1 row_mask:0xf bank_mask:0xf
	v_mov_b32_dpp v85, v74 row_ror:2 row_mask:0xf bank_mask:0xf
	v_mul_f32_e32 v74, v76, v87
	v_mov_b32_dpp v84, v78 row_shr:2 row_mask:0xf bank_mask:0xf
	v_mov_b32_dpp v92, v79 row_shr:1 row_mask:0xf bank_mask:0xf
	v_mov_b32_dpp v93, v74 row_ror:1 row_mask:0xf bank_mask:0xf
	v_mov_b32_dpp v86, v74 row_ror:2 row_mask:0xf bank_mask:0xf
	v_mul_f32_e32 v74, v77, v87
	v_mov_b32_e32 v87, v179
	v_mov_b32_dpp v85, v79 row_shr:2 row_mask:0xf bank_mask:0xf
	v_mov_b32_dpp v94, v74 row_ror:1 row_mask:0xf bank_mask:0xf
	v_mov_b32_dpp v87, v74 row_ror:2 row_mask:0xf bank_mask:0xf
	v_mov_b32_dpp v93, v80 row_shr:1 row_mask:0xf bank_mask:0xf
	v_mov_b32_dpp v86, v80 row_shr:2 row_mask:0xf bank_mask:0xf
	v_mov_b32_dpp v94, v81 row_shr:1 row_mask:0xf bank_mask:0xf
	v_mov_b32_dpp v87, v81 row_shr:2 row_mask:0xf bank_mask:0xf

; __device__ __forceinline__ float dpp_shr1(float old, float src) { return __builtin_bit_cast(float, __builtin_amdgcn_update_dpp(__builtin_bit_cast(int, old), __builtin_bit_cast(int, src), 0x111, 0xf, 0xf, false)); }
; __device__ __forceinline__ float dpp_shr2(float old, float src) { return __builtin_bit_cast(float, __builtin_amdgcn_update_dpp(__builtin_bit_cast(int, old), __builtin_bit_cast(int, src), 0x112, 0xf, 0xf, false)); }
; __device__ __forceinline__ float dpp_ror1(float src) { return __builtin_bit_cast(float, __builtin_amdgcn_update_dpp(0, __builtin_bit_cast(int, src), 0x121, 0xf, 0xf, false)); }
;     __device__ __forceinline__ void operator()(const f32x4 (&acc)[2][2][4][2], const Unit& u, int wr, int wc, int fr, int fq) const {
;     ...
;                     const float rsm = RS[16 * m]; const f32x4 g = acc[ai][0][m][n] * rsm, uu = acc[ai][1][m][n] * rsm; f32x4 p1, p2, av;
;                     if (!sample) {
; #pragma unroll
;                         for (int e = 0; e < 4; ++e) { float o1, o2;
;                             if (m == 0) { o1 = bm1[e]; o2 = (fr == 0) ? bm2[e] : bm1[e]; } else { const float gp = acc[ai][0][m > 0 ? m - 1 : 0][n][e] * RS[16 * (m > 0 ? m - 1 : 0)]; o1 = dpp_ror1(gp); o2 = dpp_ror2(gp); }
;                             p1[e] = dpp_shr1(o1, g[e]); p2[e] = dpp_shr2(o2, g[e]); }
;                         if (ai == 0 && wr == 0 && m == 0 && fr < 2 && (u.pm & 7) != 0) {
;                             *(f32x4*)(fix + ((size_t)(72 + u.pm * 2 + fr)) * DFF + j0 + 4 * n) = g; *(f32x4*)(fix + ((size_t)(144 + u.pm * 2 + fr)) * DFF + j0 + 4 * n) = uu; }
;                     } else {
;                         const int t = fr & 7, bs = (r - MP) >> 3; f32x4 s0 = (f32x4){0.f, 0.f, 0.f, 0.f}, s1 = s0;
;                         if (t < 2) { s0 = *(const f32x4*)(st_ffn + ((size_t)bs * 2 + 0) * DFF + j0 + 4 * n); s1 = *(const f32x4*)(st_ffn + ((size_t)bs * 2 + 1) * DFF + j0 + 4 * n); }
; #pragma unroll
;                         for (int e = 0; e < 4; ++e) { const float a1 = dpp_shr1(0.f, g[e]), a2 = dpp_shr2(0.f, g[e]); p1[e] = (t >= 1) ? a1 : s1[e]; p2[e] = (t >= 2) ? a2 : (t == 1 ? s1[e] : s0[e]); }
;                         if (t >= 6) *(f32x4*)(out + O_SFFN + ((size_t)bs * 2 + (t - 6)) * DFF + j0 + 4 * n) = g;
.LBB0_820:
	s_or_b64 exec, exec, s[80:81]
	v_mov_b32_e32 v84, v237
	v_add_u32_e32 v85, s74, v217
	s_mov_b64 s[86:87], -1
	s_mov_b64 s[78:79], 0
	s_and_b64 vcc, exec, s[16:17]
	s_waitcnt lgkmcnt(0)
	v_pk_mul_f32 v[106:107], v[64:65], v[84:85] op_sel_hi:[1,0]
	v_pk_mul_f32 v[104:105], v[62:63], v[84:85] op_sel_hi:[1,0]
	s_mov_b64 s[80:81], 0
	s_cbranch_vccnz .LBB0_826
	v_add_u32_e32 v80, 0xffffe000, v85
	v_ashrrev_i32_e32 v96, 3, v80
	v_mov_b32_e32 v130, 0
	v_mov_b32_e32 v131, 0
	v_mov_b32_e32 v132, 0
	v_mov_b32_e32 v133, 0
	v_mov_b32_e32 v134, 0
	v_mov_b32_e32 v135, 0
	v_mov_b32_e32 v136, 0
	v_mov_b32_e32 v137, 0
	s_and_saveexec_b64 s[80:81], s[14:15]
	s_cbranch_execz .LBB0_823
	v_mov_b64_e32 v[80:81], s[36:37]
	v_mad_i64_i32 v[80:81], s[82:83], v96, s53, v[80:81]
	v_lshl_add_u64 v[80:81], v[184:185], 2, v[80:81]
	v_add_co_u32_e32 v100, vcc, 0xa000, v80
	s_nop 1
	v_addc_co_u32_e32 v101, vcc, 0, v81, vcc
	global_load_dwordx4 v[130:133], v[80:81], off offset:16
	global_load_dwordx4 v[134:137], v[100:101], off offset:3088
.LBB0_823:
	s_or_b64 exec, exec, s[80:81]
	v_mov_b32_dpp v100, v104 row_shr:1 row_mask:0xf bank_mask:0xf bound_ctrl:1
	v_mov_b32_dpp v116, v104 row_shr:2 row_mask:0xf bank_mask:0xf bound_ctrl:1
	v_mov_b32_dpp v117, v105 row_shr:1 row_mask:0xf bank_mask:0xf bound_ctrl:1
	v_mov_b32_dpp v124, v105 row_shr:2 row_mask:0xf bank_mask:0xf bound_ctrl:1
	v_mov_b32_dpp v125, v106 row_shr:1 row_mask:0xf bank_mask:0xf bound_ctrl:1
	v_mov_b32_dpp v138, v106 row_shr:2 row_mask:0xf bank_mask:0xf bound_ctrl:1
	v_mov_b32_dpp v139, v107 row_shr:1 row_mask:0xf bank_mask:0xf bound_ctrl:1
	v_mov_b32_dpp v101, v107 row_shr:2 row_mask:0xf bank_mask:0xf bound_ctrl:1
	s_mov_b64 s[86:87], 0
	s_mov_b64 s[80:81], 0
	s_and_saveexec_b64 s[84:85], s[12:13]
	v_ashrrev_i32_e32 v97, 31, v96
	s_mov_b64 s[80:81], exec
	v_lshl_add_u64 v[80:81], v[96:97], 1, v[178:179]
	s_mov_b64 s[82:83], s[34:35]
	s_or_b64 exec, exec, s[84:85]
	s_waitcnt vmcnt(0)
	v_cndmask_b32_e64 v96, v130, v134, s[8:9]
	v_cndmask_b32_e64 v122, v100, v134, s[10:11]
	v_cndmask_b32_e64 v96, v96, v116, s[6:7]
	v_cndmask_b32_e64 v97, v131, v135, s[8:9]
	v_cndmask_b32_e64 v100, v132, v136, s[8:9]
	v_cndmask_b32_e64 v116, v133, v137, s[8:9]
	v_cndmask_b32_e64 v123, v117, v135, s[10:11]
	v_cndmask_b32_e64 v97, v97, v124, s[6:7]
	v_cndmask_b32_e64 v124, v125, v136, s[10:11]
	v_cndmask_b32_e64 v100, v100, v138, s[6:7]
	v_cndmask_b32_e64 v125, v139, v137, s[10:11]
	v_cndmask_b32_e64 v101, v116, v101, s[6:7]

; __device__ __forceinline__ unsigned cvt_pk_bf16(float lo, float hi) { unsigned r; asm volatile("v_cvt_pk_bf16_f32 %0, %1, %2" : "=v"(r) : "v"(lo), "v"(hi)); return r; }
;     __device__ __forceinline__ void operator()(const f32x4 (&acc)[2][2][4][2], const Unit& u, int wr, int wc, int fr, int fq) const {
;     ...
;                     const float rsm = RS[16 * m]; const f32x4 g = acc[ai][0][m][n] * rsm, uu = acc[ai][1][m][n] * rsm; f32x4 p1, p2, av;
;                     if (!sample) {
; #pragma unroll
;                         for (int e = 0; e < 4; ++e) { float o1, o2;
;                             if (m == 0) { o1 = bm1[e]; o2 = (fr == 0) ? bm2[e] : bm1[e]; } else { const float gp = acc[ai][0][m > 0 ? m - 1 : 0][n][e] * RS[16 * (m > 0 ? m - 1 : 0)]; o1 = dpp_ror1(gp); o2 = dpp_ror2(gp); }
;                             p1[e] = dpp_shr1(o1, g[e]); p2[e] = dpp_shr2(o2, g[e]); }
;                         if (ai == 0 && wr == 0 && m == 0 && fr < 2 && (u.pm & 7) != 0) {
;                             *(f32x4*)(fix + ((size_t)(72 + u.pm * 2 + fr)) * DFF + j0 + 4 * n) = g; *(f32x4*)(fix + ((size_t)(144 + u.pm * 2 + fr)) * DFF + j0 + 4 * n) = uu; }
;                     } else {
;                         const int t = fr & 7, bs = (r - MP) >> 3; f32x4 s0 = (f32x4){0.f, 0.f, 0.f, 0.f}, s1 = s0;
;                         if (t < 2) { s0 = *(const f32x4*)(st_ffn + ((size_t)bs * 2 + 0) * DFF + j0 + 4 * n); s1 = *(const f32x4*)(st_ffn + ((size_t)bs * 2 + 1) * DFF + j0 + 4 * n); }
; #pragma unroll
;                         for (int e = 0; e < 4; ++e) { const float a1 = dpp_shr1(0.f, g[e]), a2 = dpp_shr2(0.f, g[e]); p1[e] = (t >= 1) ? a1 : s1[e]; p2[e] = (t >= 2) ? a2 : (t == 1 ? s1[e] : s0[e]); }
;                         if (t >= 6) *(f32x4*)(out + O_SFFN + ((size_t)bs * 2 + (t - 6)) * DFF + j0 + 4 * n) = g;
;                     }
;                     const f32x4 gc = bb + w0 * p2 + w1 * p1 + w2 * g;
; #pragma unroll
;                     for (int e = 0; e < 4; ++e) av[e] = silu_e(gc[e]) * uu[e];
;                     if (n == 0) { keep[ai][m].x = cvt_pk_bf16(av[0], av[1]); keep[ai][m].y = cvt_pk_bf16(av[2], av[3]); }
;                     else { u32x4e w; w.x = keep[ai][m].x; w.y = keep[ai][m].y; w.z = cvt_pk_bf16(av[0], av[1]); w.w = cvt_pk_bf16(av[2], av[3]); *(u32x4e*)(ACT + act_off(r, j0)) = w; }
.LBB0_832:
	s_or_b64 exec, exec, s[20:21]
	s_and_saveexec_b64 s[20:21], s[78:79]
	v_mov_b64_e32 v[124:125], v[4:5]
	v_mov_b64_e32 v[122:123], v[2:3]
	v_mov_b32_e32 v96, v212
	v_mov_b32_e32 v97, v213
	v_mov_b32_e32 v100, v214
	v_mov_b32_e32 v101, v215
	s_or_b64 exec, exec, s[20:21]
	v_mov_b32_e32 v80, v89
	v_mov_b32_e32 v81, v95
	v_mov_b32_e32 v108, v107
	v_mov_b32_e32 v109, v125
	v_pk_mul_f32 v[108:109], v[80:81], v[108:109]
	v_fma_f32 v84, v75, v101, v79
	v_add_f32_e32 v84, v109, v84
	v_add_f32_e32 v84, v108, v84
	v_mul_f32_e32 v89, 0xbfb8aa3b, v84
	v_exp_f32_e32 v89, v89
	v_mov_b32_e32 v107, v124
	v_fma_f32 v100, v74, v100, v78
	v_mov_b32_e32 v108, v87
	v_add_f32_e32 v89, 1.0, v89
	v_rcp_f32_e32 v101, v89
	v_mov_b32_e32 v89, v94
	v_pk_mul_f32 v[94:95], v[88:89], v[106:107]
	v_mov_b32_e32 v109, v93
	v_add_f32_e32 v95, v95, v100
	v_add_f32_e32 v100, v94, v95
	v_mul_f32_e32 v94, 0xbfb8aa3b, v100
	v_exp_f32_e32 v94, v94
	v_mul_f32_e32 v84, v84, v101
	v_mul_f32_e32 v69, v69, v84
	v_mov_b32_e32 v95, v123
	v_add_f32_e32 v84, 1.0, v94
	v_mov_b32_e32 v94, v105
	v_pk_mul_f32 v[94:95], v[108:109], v[94:95]
	v_fma_f32 v87, v73, v97, v77
	v_add_f32_e32 v87, v95, v87
	v_add_f32_e32 v94, v94, v87
	v_mul_f32_e32 v87, 0xbfb8aa3b, v94
	v_exp_f32_e32 v95, v87
	v_mov_b32_e32 v87, v92
	v_mov_b32_e32 v105, v122
	v_pk_mul_f32 v[92:93], v[86:87], v[104:105]
	v_fma_f32 v96, v72, v96, v76
	v_add_f32_e32 v93, v93, v96
	v_add_f32_e32 v92, v92, v93
	v_mul_f32_e32 v93, 0xbfb8aa3b, v92
	v_exp_f32_e32 v93, v93
	v_rcp_f32_e32 v84, v84
	v_add_f32_e32 v95, 1.0, v95
	v_rcp_f32_e32 v95, v95
	v_add_f32_e32 v93, 1.0, v93
	v_rcp_f32_e32 v93, v93
	v_mul_f32_e32 v84, v100, v84
	v_mul_f32_e32 v68, v68, v84
	v_mul_f32_e32 v84, v94, v95
	v_mul_f32_e32 v67, v67, v84
	v_mul_f32_e32 v84, v92, v93
	v_mul_f32_e32 v66, v66, v84
	v_ashrrev_i32_e32 v125, 6, v184
	v_cvt_pk_bf16_f32 v122, v66, v67
	v_lshrrev_b32_e32 v66, 8, v85
	v_mad_i32_i24 v66, v66, s60, v125
	v_cvt_pk_bf16_f32 v123, v68, v69
	v_ashrrev_i32_e32 v67, 31, v66
	v_mov_b32_e32 v84, v238
	v_lshlrev_b64 v[66:67], 15, v[66:67]
	v_lshlrev_b32_e32 v68, 7, v217
	v_and_b32_e32 v106, 56, v216
	v_lshl_add_u64 v[66:67], s[40:41], 0, v[66:67]
	v_and_b32_e32 v68, 0x7f80, v68
	v_mov_b32_e32 v69, v179
	v_lshl_add_u64 v[66:67], v[66:67], 0, v[68:69]
	v_lshlrev_b32_e32 v110, 1, v106
	v_mov_b32_e32 v111, v179
	v_lshl_add_u64 v[66:67], v[66:67], 0, v[110:111]
	global_store_dwordx4 v[66:67], v[120:123], off
	v_add_u32_e32 v100, s74, v164
	s_waitcnt lgkmcnt(0)
	v_pk_mul_f32 v[68:69], v[56:57], v[84:85] op_sel_hi:[1,0]
	v_pk_mul_f32 v[66:67], v[54:55], v[84:85] op_sel_hi:[1,0]
	s_and_b64 vcc, exec, s[16:17]
	s_mov_b64 s[20:21], -1
	s_cbranch_vccnz .LBB0_840
	v_add_u32_e32 v85, 0xffffe000, v100
	v_ashrrev_i32_e32 v92, 3, v85
	v_mov_b32_e32 v94, 0
	v_mov_b32_e32 v95, 0
	v_mov_b32_e32 v96, 0
	v_mov_b32_e32 v97, 0
	v_mov_b32_e32 v104, 0
	v_mov_b32_e32 v105, 0
	v_mov_b32_e32 v106, 0
	v_mov_b32_e32 v107, 0
	s_and_saveexec_b64 s[20:21], s[14:15]
	s_cbranch_execz .LBB0_837
	v_mov_b64_e32 v[94:95], s[36:37]
	v_mad_i64_i32 v[94:95], s[76:77], v92, s53, v[94:95]
	v_lshl_add_u64 v[94:95], v[184:185], 2, v[94:95]
	v_add_co_u32_e32 v104, vcc, 0xa000, v94
	s_nop 1
	v_addc_co_u32_e32 v105, vcc, 0, v95, vcc
	global_load_dwordx4 v[94:97], v[94:95], off offset:16
	s_nop 0
	global_load_dwordx4 v[104:107], v[104:105], off offset:3088
.LBB0_837:
	s_or_b64 exec, exec, s[20:21]
	v_mov_b32_dpp v101, v66 row_shr:1 row_mask:0xf bank_mask:0xf bound_ctrl:1
	v_mov_b32_dpp v111, v66 row_shr:2 row_mask:0xf bank_mask:0xf bound_ctrl:1
	v_mov_b32_dpp v116, v67 row_shr:1 row_mask:0xf bank_mask:0xf bound_ctrl:1
	v_mov_b32_dpp v117, v67 row_shr:2 row_mask:0xf bank_mask:0xf bound_ctrl:1
	v_mov_b32_dpp v120, v68 row_shr:1 row_mask:0xf bank_mask:0xf bound_ctrl:1
	v_mov_b32_dpp v121, v68 row_shr:2 row_mask:0xf bank_mask:0xf bound_ctrl:1
	v_mov_b32_dpp v122, v69 row_shr:1 row_mask:0xf bank_mask:0xf bound_ctrl:1
	v_mov_b32_dpp v85, v69 row_shr:2 row_mask:0xf bank_mask:0xf bound_ctrl:1
	s_and_saveexec_b64 s[20:21], s[12:13]
	s_cbranch_execz .LBB0_839
	v_ashrrev_i32_e32 v93, 31, v92
	v_lshl_add_u64 v[92:93], v[92:93], 1, v[178:179]
	v_mov_b64_e32 v[126:127], s[34:35]
	v_mad_u64_u32 v[126:127], s[76:77], v92, s26, v[126:127]
	v_mad_i32_i24 v127, v93, s26, v127
	v_lshl_add_u64 v[92:93], v[184:185], 2, v[126:127]
	v_add_co_u32_e32 v92, vcc, 0x15c86000, v92
	s_nop 1
	v_addc_co_u32_e32 v93, vcc, 0, v93, vcc
	global_store_dwordx4 v[92:93], v[66:69], off offset:16

; __device__ __forceinline__ unsigned cvt_pk_bf16(float lo, float hi) { unsigned r; asm volatile("v_cvt_pk_bf16_f32 %0, %1, %2" : "=v"(r) : "v"(lo), "v"(hi)); return r; }
;     __device__ __forceinline__ void operator()(const f32x4 (&acc)[2][2][4][2], const Unit& u, int wr, int wc, int fr, int fq) const {
;     ...
;                     const float rsm = RS[16 * m]; const f32x4 g = acc[ai][0][m][n] * rsm, uu = acc[ai][1][m][n] * rsm; f32x4 p1, p2, av;
;                     if (!sample) {
; #pragma unroll
;                         for (int e = 0; e < 4; ++e) { float o1, o2;
;                             if (m == 0) { o1 = bm1[e]; o2 = (fr == 0) ? bm2[e] : bm1[e]; } else { const float gp = acc[ai][0][m > 0 ? m - 1 : 0][n][e] * RS[16 * (m > 0 ? m - 1 : 0)]; o1 = dpp_ror1(gp); o2 = dpp_ror2(gp); }
;                             p1[e] = dpp_shr1(o1, g[e]); p2[e] = dpp_shr2(o2, g[e]); }
;                         if (ai == 0 && wr == 0 && m == 0 && fr < 2 && (u.pm & 7) != 0) {
;                             *(f32x4*)(fix + ((size_t)(72 + u.pm * 2 + fr)) * DFF + j0 + 4 * n) = g; *(f32x4*)(fix + ((size_t)(144 + u.pm * 2 + fr)) * DFF + j0 + 4 * n) = uu; }
;                     } else {
;                         const int t = fr & 7, bs = (r - MP) >> 3; f32x4 s0 = (f32x4){0.f, 0.f, 0.f, 0.f}, s1 = s0;
;                         if (t < 2) { s0 = *(const f32x4*)(st_ffn + ((size_t)bs * 2 + 0) * DFF + j0 + 4 * n); s1 = *(const f32x4*)(st_ffn + ((size_t)bs * 2 + 1) * DFF + j0 + 4 * n); }
; #pragma unroll
;                         for (int e = 0; e < 4; ++e) { const float a1 = dpp_shr1(0.f, g[e]), a2 = dpp_shr2(0.f, g[e]); p1[e] = (t >= 1) ? a1 : s1[e]; p2[e] = (t >= 2) ? a2 : (t == 1 ? s1[e] : s0[e]); }
;                         if (t >= 6) *(f32x4*)(out + O_SFFN + ((size_t)bs * 2 + (t - 6)) * DFF + j0 + 4 * n) = g;
;                     }
;                     const f32x4 gc = bb + w0 * p2 + w1 * p1 + w2 * g;
; #pragma unroll
;                     for (int e = 0; e < 4; ++e) av[e] = silu_e(gc[e]) * uu[e];
;                     if (n == 0) { keep[ai][m].x = cvt_pk_bf16(av[0], av[1]); keep[ai][m].y = cvt_pk_bf16(av[2], av[3]); }
;                     else { u32x4e w; w.x = keep[ai][m].x; w.y = keep[ai][m].y; w.z = cvt_pk_bf16(av[0], av[1]); w.w = cvt_pk_bf16(av[2], av[3]); *(u32x4e*)(ACT + act_off(r, j0)) = w; }
.LBB0_840:
	s_and_b64 vcc, exec, s[20:21]
	s_cbranch_vccz .LBB0_842
	v_mov_b32_e32 v85, v237
	v_mov_b32_e32 v92, v179
	v_mov_b32_e32 v101, v179
	v_mov_b32_e32 v93, v179
	v_mov_b32_e32 v104, v179
	s_waitcnt lgkmcnt(0)
	v_mul_f32_e32 v62, v62, v85
	v_mov_b32_e32 v94, v179
	v_mov_b32_e32 v96, v179
	v_mov_b32_dpp v92, v62 row_ror:1 row_mask:0xf bank_mask:0xf
	v_mov_b32_dpp v101, v62 row_ror:2 row_mask:0xf bank_mask:0xf
	v_mul_f32_e32 v62, v63, v85
	v_mov_b32_e32 v95, v179
	v_mov_b32_e32 v97, v179
	v_mov_b32_dpp v93, v62 row_ror:1 row_mask:0xf bank_mask:0xf
	v_mov_b32_dpp v104, v62 row_ror:2 row_mask:0xf bank_mask:0xf
	v_mul_f32_e32 v62, v64, v85
	v_mov_b32_dpp v92, v66 row_shr:1 row_mask:0xf bank_mask:0xf
	v_mov_b32_dpp v101, v66 row_shr:2 row_mask:0xf bank_mask:0xf
	v_mov_b32_dpp v94, v62 row_ror:1 row_mask:0xf bank_mask:0xf
	v_mov_b32_dpp v96, v62 row_ror:2 row_mask:0xf bank_mask:0xf
	v_mul_f32_e32 v62, v65, v85
	v_mov_b32_dpp v93, v67 row_shr:1 row_mask:0xf bank_mask:0xf
	v_mov_b32_dpp v104, v67 row_shr:2 row_mask:0xf bank_mask:0xf
	v_mov_b32_dpp v95, v62 row_ror:1 row_mask:0xf bank_mask:0xf
	v_mov_b32_dpp v97, v62 row_ror:2 row_mask:0xf bank_mask:0xf
	v_mov_b32_dpp v94, v68 row_shr:1 row_mask:0xf bank_mask:0xf
	v_mov_b32_dpp v96, v68 row_shr:2 row_mask:0xf bank_mask:0xf
	v_mov_b32_dpp v95, v69 row_shr:1 row_mask:0xf bank_mask:0xf
	v_mov_b32_dpp v97, v69 row_shr:2 row_mask:0xf bank_mask:0xf
.LBB0_842:
	v_mov_b32_e32 v62, v69
	v_mov_b32_e32 v63, v95
	v_pk_mul_f32 v[62:63], v[80:81], v[62:63]
	v_fma_f32 v64, v75, v97, v79
	v_add_f32_e32 v63, v63, v64
	v_add_f32_e32 v64, v62, v63
	v_mul_f32_e32 v62, 0xbfb8aa3b, v64
	v_exp_f32_e32 v65, v62
	v_mov_b32_e32 v62, v84
	v_mov_b32_e32 v63, v84
	v_pk_mul_f32 v[60:61], v[60:61], v[62:63]
	v_add_f32_e32 v62, 1.0, v65
	v_mov_b32_e32 v69, v94
	v_rcp_f32_e32 v65, v62
	v_pk_mul_f32 v[62:63], v[88:89], v[68:69]
	v_fma_f32 v68, v74, v96, v78
	v_add_f32_e32 v63, v63, v68
	v_add_f32_e32 v68, v62, v63
	v_mul_f32_e32 v62, 0xbfb8aa3b, v68
	v_exp_f32_e32 v62, v62
	v_mul_f32_e32 v63, v64, v65
	v_mul_f32_e32 v61, v61, v63
	v_mov_b32_e32 v63, v93
	v_add_f32_e32 v62, 1.0, v62
	v_rcp_f32_e32 v64, v62
	v_mov_b32_e32 v62, v67
	v_pk_mul_f32 v[62:63], v[108:109], v[62:63]
	v_fma_f32 v65, v73, v104, v77
	v_add_f32_e32 v63, v63, v65
	v_add_f32_e32 v65, v62, v63
	v_mul_f32_e32 v62, 0xbfb8aa3b, v65
	v_mov_b32_e32 v67, v92
	v_exp_f32_e32 v69, v62
	v_pk_mul_f32 v[62:63], v[86:87], v[66:67]
	v_fma_f32 v66, v72, v101, v76
	v_add_f32_e32 v63, v63, v66
	v_add_f32_e32 v62, v62, v63
	v_mul_f32_e32 v63, 0xbfb8aa3b, v62
	v_exp_f32_e32 v63, v63
	v_add_f32_e32 v66, 1.0, v69
	v_rcp_f32_e32 v66, v66
	v_mov_b32_e32 v85, v84
	v_add_f32_e32 v63, 1.0, v63
	v_rcp_f32_e32 v63, v63
	v_pk_mul_f32 v[58:59], v[58:59], v[84:85]
	v_mul_f32_e32 v64, v68, v64
	v_mul_f32_e32 v60, v60, v64
	v_mul_f32_e32 v62, v62, v63
	v_mul_f32_e32 v64, v65, v66
	v_mul_f32_e32 v58, v58, v62
	v_mul_f32_e32 v59, v59, v64
	v_cvt_pk_bf16_f32 v120, v58, v59
	v_lshrrev_b32_e32 v58, 8, v100
	v_mad_i32_i24 v58, v58, s60, v125
	v_cvt_pk_bf16_f32 v121, v60, v61
	v_ashrrev_i32_e32 v59, 31, v58
	v_mov_b32_e32 v68, v239
	v_lshlrev_b64 v[58:59], 15, v[58:59]
	v_lshlrev_b32_e32 v60, 7, v164
	v_lshl_add_u64 v[58:59], s[40:41], 0, v[58:59]
	v_and_b32_e32 v60, 0x7f80, v60
	v_mov_b32_e32 v61, v179
	v_lshl_add_u64 v[58:59], v[58:59], 0, v[60:61]
	v_mov_b32_e32 v111, v179
	v_lshl_add_u64 v[58:59], v[58:59], 0, v[110:111]
	global_store_dwordx4 v[58:59], v[118:121], off
	v_add_u32_e32 v84, s74, v158
	s_waitcnt lgkmcnt(0)
	v_pk_mul_f32 v[60:61], v[44:45], v[68:69] op_sel_hi:[1,0]
	v_pk_mul_f32 v[58:59], v[42:43], v[68:69] op_sel_hi:[1,0]
	s_and_b64 vcc, exec, s[16:17]
	s_mov_b64 s[20:21], -1
	s_cbranch_vccnz .LBB0_848
	v_add_u32_e32 v62, 0xffffe000, v84
	v_ashrrev_i32_e32 v62, 3, v62
	v_mov_b32_e32 v64, 0
	v_mov_b32_e32 v65, 0
	v_mov_b32_e32 v66, 0
	v_mov_b32_e32 v67, 0
	v_mov_b32_e32 v92, 0
	v_mov_b32_e32 v93, 0
	v_mov_b32_e32 v94, 0
	v_mov_b32_e32 v95, 0
	s_and_saveexec_b64 s[20:21], s[14:15]
	s_cbranch_execz .LBB0_845
	v_mov_b64_e32 v[64:65], s[36:37]
	v_mad_i64_i32 v[64:65], s[76:77], v62, s53, v[64:65]
	v_lshl_add_u64 v[64:65], v[184:185], 2, v[64:65]
	v_add_co_u32_e32 v92, vcc, 0xa000, v64
	s_nop 1
	v_addc_co_u32_e32 v93, vcc, 0, v65, vcc
	global_load_dwordx4 v[64:67], v[64:65], off offset:16
	s_nop 0
	global_load_dwordx4 v[92:95], v[92:93], off offset:3088
.LBB0_845:
	s_or_b64 exec, exec, s[20:21]
	v_mov_b32_dpp v85, v58 row_shr:1 row_mask:0xf bank_mask:0xf bound_ctrl:1
	v_mov_b32_dpp v96, v58 row_shr:2 row_mask:0xf bank_mask:0xf bound_ctrl:1
	v_mov_b32_dpp v97, v59 row_shr:1 row_mask:0xf bank_mask:0xf bound_ctrl:1
	v_mov_b32_dpp v100, v59 row_shr:2 row_mask:0xf bank_mask:0xf bound_ctrl:1
	v_mov_b32_dpp v101, v60 row_shr:1 row_mask:0xf bank_mask:0xf bound_ctrl:1
	v_mov_b32_dpp v104, v60 row_shr:2 row_mask:0xf bank_mask:0xf bound_ctrl:1
	v_mov_b32_dpp v105, v61 row_shr:1 row_mask:0xf bank_mask:0xf bound_ctrl:1
	v_mov_b32_dpp v69, v61 row_shr:2 row_mask:0xf bank_mask:0xf bound_ctrl:1
	s_and_saveexec_b64 s[20:21], s[12:13]
	s_cbranch_execz .LBB0_847
	v_ashrrev_i32_e32 v63, 31, v62
	v_lshl_add_u64 v[62:63], v[62:63], 1, v[178:179]
	v_mov_b64_e32 v[106:107], s[34:35]
	v_mad_u64_u32 v[106:107], s[76:77], v62, s26, v[106:107]
	v_mad_i32_i24 v107, v63, s26, v107
	v_lshl_add_u64 v[62:63], v[184:185], 2, v[106:107]
	v_add_co_u32_e32 v62, vcc, 0x15c86000, v62
	s_nop 1
	v_addc_co_u32_e32 v63, vcc, 0, v63, vcc
	global_store_dwordx4 v[62:63], v[58:61], off offset:16

; __device__ __forceinline__ unsigned cvt_pk_bf16(float lo, float hi) { unsigned r; asm volatile("v_cvt_pk_bf16_f32 %0, %1, %2" : "=v"(r) : "v"(lo), "v"(hi)); return r; }
;     __device__ __forceinline__ void operator()(const f32x4 (&acc)[2][2][4][2], const Unit& u, int wr, int wc, int fr, int fq) const {
;     ...
;                     const float rsm = RS[16 * m]; const f32x4 g = acc[ai][0][m][n] * rsm, uu = acc[ai][1][m][n] * rsm; f32x4 p1, p2, av;
;                     if (!sample) {
; #pragma unroll
;                         for (int e = 0; e < 4; ++e) { float o1, o2;
;                             if (m == 0) { o1 = bm1[e]; o2 = (fr == 0) ? bm2[e] : bm1[e]; } else { const float gp = acc[ai][0][m > 0 ? m - 1 : 0][n][e] * RS[16 * (m > 0 ? m - 1 : 0)]; o1 = dpp_ror1(gp); o2 = dpp_ror2(gp); }
;                             p1[e] = dpp_shr1(o1, g[e]); p2[e] = dpp_shr2(o2, g[e]); }
;                         if (ai == 0 && wr == 0 && m == 0 && fr < 2 && (u.pm & 7) != 0) {
;                             *(f32x4*)(fix + ((size_t)(72 + u.pm * 2 + fr)) * DFF + j0 + 4 * n) = g; *(f32x4*)(fix + ((size_t)(144 + u.pm * 2 + fr)) * DFF + j0 + 4 * n) = uu; }
;                     } else {
;                         const int t = fr & 7, bs = (r - MP) >> 3; f32x4 s0 = (f32x4){0.f, 0.f, 0.f, 0.f}, s1 = s0;
;                         if (t < 2) { s0 = *(const f32x4*)(st_ffn + ((size_t)bs * 2 + 0) * DFF + j0 + 4 * n); s1 = *(const f32x4*)(st_ffn + ((size_t)bs * 2 + 1) * DFF + j0 + 4 * n); }
; #pragma unroll
;                         for (int e = 0; e < 4; ++e) { const float a1 = dpp_shr1(0.f, g[e]), a2 = dpp_shr2(0.f, g[e]); p1[e] = (t >= 1) ? a1 : s1[e]; p2[e] = (t >= 2) ? a2 : (t == 1 ? s1[e] : s0[e]); }
;                         if (t >= 6) *(f32x4*)(out + O_SFFN + ((size_t)bs * 2 + (t - 6)) * DFF + j0 + 4 * n) = g;
;                     }
;                     const f32x4 gc = bb + w0 * p2 + w1 * p1 + w2 * g;
; #pragma unroll
;                     for (int e = 0; e < 4; ++e) av[e] = silu_e(gc[e]) * uu[e];
;                     if (n == 0) { keep[ai][m].x = cvt_pk_bf16(av[0], av[1]); keep[ai][m].y = cvt_pk_bf16(av[2], av[3]); }
;                     else { u32x4e w; w.x = keep[ai][m].x; w.y = keep[ai][m].y; w.z = cvt_pk_bf16(av[0], av[1]); w.w = cvt_pk_bf16(av[2], av[3]); *(u32x4e*)(ACT + act_off(r, j0)) = w; }
.LBB0_848:
	s_and_b64 vcc, exec, s[20:21]
	s_cbranch_vccz .LBB0_850
	v_mov_b32_e32 v65, v238
	v_mov_b32_e32 v62, v179
	v_mov_b32_e32 v85, v179
	v_mov_b32_e32 v63, v179
	v_mov_b32_e32 v92, v179
	s_waitcnt lgkmcnt(0)
	v_mul_f32_e32 v54, v54, v65
	v_mov_b32_e32 v64, v179
	v_mov_b32_e32 v66, v179
	v_mov_b32_dpp v62, v54 row_ror:1 row_mask:0xf bank_mask:0xf
	v_mov_b32_dpp v85, v54 row_ror:2 row_mask:0xf bank_mask:0xf
	v_mul_f32_e32 v54, v55, v65
	v_mov_b32_e32 v67, v179
	v_mov_b32_dpp v62, v58 row_shr:1 row_mask:0xf bank_mask:0xf
	v_mov_b32_dpp v63, v54 row_ror:1 row_mask:0xf bank_mask:0xf
	v_mov_b32_dpp v92, v54 row_ror:2 row_mask:0xf bank_mask:0xf
	v_mul_f32_e32 v54, v56, v65
	v_mov_b32_dpp v85, v58 row_shr:2 row_mask:0xf bank_mask:0xf
	v_mov_b32_dpp v63, v59 row_shr:1 row_mask:0xf bank_mask:0xf
	v_mov_b32_dpp v64, v54 row_ror:1 row_mask:0xf bank_mask:0xf
	v_mov_b32_dpp v66, v54 row_ror:2 row_mask:0xf bank_mask:0xf
	v_mul_f32_e32 v54, v57, v65
	v_mov_b32_e32 v65, v179
	v_mov_b32_dpp v92, v59 row_shr:2 row_mask:0xf bank_mask:0xf
	v_mov_b32_dpp v67, v54 row_ror:2 row_mask:0xf bank_mask:0xf
	v_mov_b32_dpp v65, v54 row_ror:1 row_mask:0xf bank_mask:0xf
	v_mov_b32_dpp v64, v60 row_shr:1 row_mask:0xf bank_mask:0xf
	v_mov_b32_dpp v66, v60 row_shr:2 row_mask:0xf bank_mask:0xf
	v_mov_b32_dpp v65, v61 row_shr:1 row_mask:0xf bank_mask:0xf
	v_mov_b32_dpp v67, v61 row_shr:2 row_mask:0xf bank_mask:0xf
.LBB0_850:
	v_mov_b32_e32 v54, v61
	v_mov_b32_e32 v55, v65
	v_pk_mul_f32 v[54:55], v[80:81], v[54:55]
	v_fma_f32 v56, v75, v67, v79
	v_add_f32_e32 v55, v55, v56
	v_add_f32_e32 v56, v54, v55
	v_mul_f32_e32 v54, 0xbfb8aa3b, v56
	v_exp_f32_e32 v57, v54
	v_mov_b32_e32 v54, v68
	v_mov_b32_e32 v55, v68
	v_pk_mul_f32 v[52:53], v[52:53], v[54:55]
	v_add_f32_e32 v54, 1.0, v57
	v_mov_b32_e32 v61, v64
	v_rcp_f32_e32 v57, v54
	v_pk_mul_f32 v[54:55], v[88:89], v[60:61]
	v_fma_f32 v60, v74, v66, v78
	v_add_f32_e32 v55, v55, v60
	v_add_f32_e32 v60, v54, v55
	v_mul_f32_e32 v54, 0xbfb8aa3b, v60
	v_exp_f32_e32 v54, v54
	v_mul_f32_e32 v55, v56, v57
	v_mul_f32_e32 v53, v53, v55
	v_mov_b32_e32 v55, v63
	v_add_f32_e32 v54, 1.0, v54
	v_rcp_f32_e32 v56, v54
	v_mov_b32_e32 v54, v59
	v_pk_mul_f32 v[54:55], v[108:109], v[54:55]
	v_fma_f32 v57, v73, v92, v77
	v_add_f32_e32 v55, v55, v57
	v_add_f32_e32 v57, v54, v55
	v_mul_f32_e32 v54, 0xbfb8aa3b, v57
	v_mov_b32_e32 v59, v62
	v_exp_f32_e32 v61, v54
	v_pk_mul_f32 v[54:55], v[86:87], v[58:59]
	v_fma_f32 v58, v72, v85, v76
	v_add_f32_e32 v55, v55, v58
	v_add_f32_e32 v54, v54, v55
	v_mul_f32_e32 v55, 0xbfb8aa3b, v54
	v_exp_f32_e32 v55, v55
	v_add_f32_e32 v58, 1.0, v61
	v_rcp_f32_e32 v58, v58
	v_mov_b32_e32 v69, v68
	v_add_f32_e32 v55, 1.0, v55
	v_rcp_f32_e32 v55, v55
	v_pk_mul_f32 v[50:51], v[50:51], v[68:69]
	v_mul_f32_e32 v56, v60, v56
	v_mul_f32_e32 v52, v52, v56
	v_mul_f32_e32 v54, v54, v55
	v_mul_f32_e32 v56, v57, v58
	v_mul_f32_e32 v50, v50, v54
	v_mul_f32_e32 v51, v51, v56
	v_cvt_pk_bf16_f32 v116, v50, v51
	v_lshrrev_b32_e32 v50, 8, v84
	v_cvt_pk_bf16_f32 v117, v52, v53
	v_mad_i32_i24 v50, v50, s60, v125
	v_mov_b32_e32 v60, v240
	v_ashrrev_i32_e32 v51, 31, v50
	v_lshlrev_b64 v[50:51], 15, v[50:51]
	v_lshlrev_b32_e32 v52, 7, v158
	v_lshl_add_u64 v[50:51], s[40:41], 0, v[50:51]
	v_and_b32_e32 v52, 0x7f80, v52
	v_mov_b32_e32 v53, v179
	v_lshl_add_u64 v[50:51], v[50:51], 0, v[52:53]
	v_mov_b32_e32 v111, v179
	v_lshl_add_u64 v[50:51], v[50:51], 0, v[110:111]
	v_add_u32_e32 v62, s74, v152
	s_waitcnt lgkmcnt(0)
	v_pk_mul_f32 v[48:49], v[48:49], v[60:61] op_sel_hi:[1,0]
	v_pk_mul_f32 v[46:47], v[46:47], v[60:61] op_sel_hi:[1,0]
	s_and_b64 vcc, exec, s[16:17]
	s_mov_b64 s[20:21], -1
	global_store_dwordx4 v[50:51], v[114:117], off
	s_cbranch_vccnz .LBB0_856
	v_add_u32_e32 v50, 0xffffe000, v62
	v_ashrrev_i32_e32 v50, 3, v50
	v_mov_b32_e32 v52, 0
	v_mov_b32_e32 v53, 0
	v_mov_b32_e32 v54, 0
	v_mov_b32_e32 v55, 0
	v_mov_b32_e32 v56, 0
	v_mov_b32_e32 v57, 0
	v_mov_b32_e32 v58, 0
	v_mov_b32_e32 v59, 0
	s_and_saveexec_b64 s[20:21], s[14:15]
	s_cbranch_execz .LBB0_853
	v_mov_b64_e32 v[52:53], s[36:37]
	v_mad_i64_i32 v[52:53], s[76:77], v50, s53, v[52:53]
	v_lshl_add_u64 v[52:53], v[184:185], 2, v[52:53]
	v_add_co_u32_e32 v56, vcc, 0xa000, v52
	s_nop 1
	v_addc_co_u32_e32 v57, vcc, 0, v53, vcc
	global_load_dwordx4 v[52:55], v[52:53], off offset:16
	s_nop 0
	global_load_dwordx4 v[56:59], v[56:57], off offset:3088
.LBB0_853:
	s_or_b64 exec, exec, s[20:21]
	v_mov_b32_dpp v63, v46 row_shr:1 row_mask:0xf bank_mask:0xf bound_ctrl:1
	v_mov_b32_dpp v64, v46 row_shr:2 row_mask:0xf bank_mask:0xf bound_ctrl:1
	v_mov_b32_dpp v65, v47 row_shr:1 row_mask:0xf bank_mask:0xf bound_ctrl:1
	v_mov_b32_dpp v66, v47 row_shr:2 row_mask:0xf bank_mask:0xf bound_ctrl:1
	v_mov_b32_dpp v67, v48 row_shr:1 row_mask:0xf bank_mask:0xf bound_ctrl:1
	v_mov_b32_dpp v68, v48 row_shr:2 row_mask:0xf bank_mask:0xf bound_ctrl:1
	v_mov_b32_dpp v69, v49 row_shr:1 row_mask:0xf bank_mask:0xf bound_ctrl:1
	v_mov_b32_dpp v61, v49 row_shr:2 row_mask:0xf bank_mask:0xf bound_ctrl:1
	s_and_saveexec_b64 s[20:21], s[12:13]
	s_cbranch_execz .LBB0_855
	v_ashrrev_i32_e32 v51, 31, v50
	v_lshl_add_u64 v[50:51], v[50:51], 1, v[178:179]
	v_mov_b64_e32 v[84:85], s[34:35]
	v_mad_u64_u32 v[84:85], s[76:77], v50, s26, v[84:85]
	v_mad_i32_i24 v85, v51, s26, v85
	v_lshl_add_u64 v[50:51], v[184:185], 2, v[84:85]
	v_add_co_u32_e32 v50, vcc, 0x15c86000, v50
	s_nop 1
	v_addc_co_u32_e32 v51, vcc, 0, v51, vcc
	global_store_dwordx4 v[50:51], v[46:49], off offset:16

; __device__ __forceinline__ float dpp_shr1(float old, float src) { return __builtin_bit_cast(float, __builtin_amdgcn_update_dpp(__builtin_bit_cast(int, old), __builtin_bit_cast(int, src), 0x111, 0xf, 0xf, false)); }
; __device__ __forceinline__ float dpp_shr2(float old, float src) { return __builtin_bit_cast(float, __builtin_amdgcn_update_dpp(__builtin_bit_cast(int, old), __builtin_bit_cast(int, src), 0x112, 0xf, 0xf, false)); }
; __device__ __forceinline__ float dpp_ror1(float src) { return __builtin_bit_cast(float, __builtin_amdgcn_update_dpp(0, __builtin_bit_cast(int, src), 0x121, 0xf, 0xf, false)); }
; __device__ __forceinline__ float dpp_ror2(float src) { return __builtin_bit_cast(float, __builtin_amdgcn_update_dpp(0, __builtin_bit_cast(int, src), 0x122, 0xf, 0xf, false)); }
;     __device__ __forceinline__ void operator()(const f32x4 (&acc)[2][2][4][2], const Unit& u, int wr, int wc, int fr, int fq) const {
;     ...
;                     const float rsm = RS[16 * m]; const f32x4 g = acc[ai][0][m][n] * rsm, uu = acc[ai][1][m][n] * rsm; f32x4 p1, p2, av;
;                     if (!sample) {
; #pragma unroll
;                         for (int e = 0; e < 4; ++e) { float o1, o2;
;                             if (m == 0) { o1 = bm1[e]; o2 = (fr == 0) ? bm2[e] : bm1[e]; } else { const float gp = acc[ai][0][m > 0 ? m - 1 : 0][n][e] * RS[16 * (m > 0 ? m - 1 : 0)]; o1 = dpp_ror1(gp); o2 = dpp_ror2(gp); }
;                             p1[e] = dpp_shr1(o1, g[e]); p2[e] = dpp_shr2(o2, g[e]); }
.LBB0_856:
	s_and_b64 vcc, exec, s[20:21]
	s_cbranch_vccz .LBB0_858
	v_mov_b32_e32 v53, v239
	v_mov_b32_e32 v50, v179
	v_mov_b32_e32 v56, v179
	v_mov_b32_e32 v51, v179
	v_mov_b32_e32 v57, v179
	s_waitcnt lgkmcnt(0)
	v_mul_f32_e32 v42, v42, v53
	v_mov_b32_e32 v52, v179
	v_mov_b32_e32 v54, v179
	v_mov_b32_dpp v50, v42 row_ror:1 row_mask:0xf bank_mask:0xf
	v_mov_b32_dpp v56, v42 row_ror:2 row_mask:0xf bank_mask:0xf
	v_mul_f32_e32 v42, v43, v53
	v_mov_b32_e32 v55, v179
	v_mov_b32_dpp v50, v46 row_shr:1 row_mask:0xf bank_mask:0xf
	v_mov_b32_dpp v51, v42 row_ror:1 row_mask:0xf bank_mask:0xf
	v_mov_b32_dpp v57, v42 row_ror:2 row_mask:0xf bank_mask:0xf
	v_mul_f32_e32 v42, v44, v53
	v_mov_b32_dpp v56, v46 row_shr:2 row_mask:0xf bank_mask:0xf
	v_mov_b32_dpp v51, v47 row_shr:1 row_mask:0xf bank_mask:0xf
	v_mov_b32_dpp v52, v42 row_ror:1 row_mask:0xf bank_mask:0xf
	v_mov_b32_dpp v54, v42 row_ror:2 row_mask:0xf bank_mask:0xf
	v_mul_f32_e32 v42, v45, v53
	v_mov_b32_e32 v53, v179
	v_mov_b32_dpp v57, v47 row_shr:2 row_mask:0xf bank_mask:0xf
	v_mov_b32_dpp v55, v42 row_ror:2 row_mask:0xf bank_mask:0xf
	v_mov_b32_dpp v53, v42 row_ror:1 row_mask:0xf bank_mask:0xf
	v_mov_b32_dpp v52, v48 row_shr:1 row_mask:0xf bank_mask:0xf
	v_mov_b32_dpp v54, v48 row_shr:2 row_mask:0xf bank_mask:0xf
	v_mov_b32_dpp v53, v49 row_shr:1 row_mask:0xf bank_mask:0xf
	v_mov_b32_dpp v55, v49 row_shr:2 row_mask:0xf bank_mask:0xf

; __device__ __forceinline__ float dpp_shr1(float old, float src) { return __builtin_bit_cast(float, __builtin_amdgcn_update_dpp(__builtin_bit_cast(int, old), __builtin_bit_cast(int, src), 0x111, 0xf, 0xf, false)); }
; __device__ __forceinline__ float dpp_shr2(float old, float src) { return __builtin_bit_cast(float, __builtin_amdgcn_update_dpp(__builtin_bit_cast(int, old), __builtin_bit_cast(int, src), 0x112, 0xf, 0xf, false)); }
; __device__ __forceinline__ float dpp_ror1(float src) { return __builtin_bit_cast(float, __builtin_amdgcn_update_dpp(0, __builtin_bit_cast(int, src), 0x121, 0xf, 0xf, false)); }
;     __device__ __forceinline__ void operator()(const f32x4 (&acc)[2][2][4][2], const Unit& u, int wr, int wc, int fr, int fq) const {
;     ...
;                     const float rsm = RS[16 * m]; const f32x4 g = acc[ai][0][m][n] * rsm, uu = acc[ai][1][m][n] * rsm; f32x4 p1, p2, av;
;                     if (!sample) {
; #pragma unroll
;                         for (int e = 0; e < 4; ++e) { float o1, o2;
;                             if (m == 0) { o1 = bm1[e]; o2 = (fr == 0) ? bm2[e] : bm1[e]; } else { const float gp = acc[ai][0][m > 0 ? m - 1 : 0][n][e] * RS[16 * (m > 0 ? m - 1 : 0)]; o1 = dpp_ror1(gp); o2 = dpp_ror2(gp); }
;                             p1[e] = dpp_shr1(o1, g[e]); p2[e] = dpp_shr2(o2, g[e]); }
;                         if (ai == 0 && wr == 0 && m == 0 && fr < 2 && (u.pm & 7) != 0) {
;                             *(f32x4*)(fix + ((size_t)(72 + u.pm * 2 + fr)) * DFF + j0 + 4 * n) = g; *(f32x4*)(fix + ((size_t)(144 + u.pm * 2 + fr)) * DFF + j0 + 4 * n) = uu; }
;                     } else {
;                         const int t = fr & 7, bs = (r - MP) >> 3; f32x4 s0 = (f32x4){0.f, 0.f, 0.f, 0.f}, s1 = s0;
;                         if (t < 2) { s0 = *(const f32x4*)(st_ffn + ((size_t)bs * 2 + 0) * DFF + j0 + 4 * n); s1 = *(const f32x4*)(st_ffn + ((size_t)bs * 2 + 1) * DFF + j0 + 4 * n); }
; #pragma unroll
;                         for (int e = 0; e < 4; ++e) { const float a1 = dpp_shr1(0.f, g[e]), a2 = dpp_shr2(0.f, g[e]); p1[e] = (t >= 1) ? a1 : s1[e]; p2[e] = (t >= 2) ? a2 : (t == 1 ? s1[e] : s0[e]); }
;                         if (t >= 6) *(f32x4*)(out + O_SFFN + ((size_t)bs * 2 + (t - 6)) * DFF + j0 + 4 * n) = g;
.LBB0_860:
	v_mov_b32_e32 v60, v241
	v_add_u32_e32 v62, s74, v151
	s_and_b64 vcc, exec, s[16:17]
	s_mov_b64 s[20:21], -1
	s_waitcnt lgkmcnt(0)
	v_pk_mul_f32 v[40:41], v[32:33], v[60:61] op_sel_hi:[1,0]
	v_pk_mul_f32 v[38:39], v[30:31], v[60:61] op_sel_hi:[1,0]
	s_cbranch_vccnz .LBB0_866
	v_add_u32_e32 v50, 0xffffe000, v62
	v_ashrrev_i32_e32 v50, 3, v50
	v_mov_b32_e32 v52, 0
	v_mov_b32_e32 v53, 0
	v_mov_b32_e32 v54, 0
	v_mov_b32_e32 v55, 0
	v_mov_b32_e32 v56, 0
	v_mov_b32_e32 v57, 0
	v_mov_b32_e32 v58, 0
	v_mov_b32_e32 v59, 0
	s_and_saveexec_b64 s[20:21], s[14:15]
	s_cbranch_execz .LBB0_863
	v_mov_b64_e32 v[52:53], s[36:37]
	v_mad_i64_i32 v[52:53], s[22:23], v50, s53, v[52:53]
	v_lshl_add_u64 v[52:53], v[184:185], 2, v[52:53]
	v_add_co_u32_e32 v56, vcc, 0xa000, v52
	s_nop 1
	v_addc_co_u32_e32 v57, vcc, 0, v53, vcc
	global_load_dwordx4 v[52:55], v[52:53], off offset:16
	s_nop 0
	global_load_dwordx4 v[56:59], v[56:57], off offset:3088
.LBB0_863:
	s_or_b64 exec, exec, s[20:21]
	v_mov_b32_dpp v63, v38 row_shr:1 row_mask:0xf bank_mask:0xf bound_ctrl:1
	v_mov_b32_dpp v64, v38 row_shr:2 row_mask:0xf bank_mask:0xf bound_ctrl:1
	v_mov_b32_dpp v65, v39 row_shr:1 row_mask:0xf bank_mask:0xf bound_ctrl:1
	v_mov_b32_dpp v66, v39 row_shr:2 row_mask:0xf bank_mask:0xf bound_ctrl:1
	v_mov_b32_dpp v67, v40 row_shr:1 row_mask:0xf bank_mask:0xf bound_ctrl:1
	v_mov_b32_dpp v68, v40 row_shr:2 row_mask:0xf bank_mask:0xf bound_ctrl:1
	v_mov_b32_dpp v69, v41 row_shr:1 row_mask:0xf bank_mask:0xf bound_ctrl:1
	v_mov_b32_dpp v61, v41 row_shr:2 row_mask:0xf bank_mask:0xf bound_ctrl:1
	s_and_saveexec_b64 s[20:21], s[12:13]
	s_cbranch_execz .LBB0_865
	v_ashrrev_i32_e32 v51, 31, v50
	v_lshl_add_u64 v[50:51], v[50:51], 1, v[178:179]
	v_mov_b64_e32 v[84:85], s[34:35]
	v_mad_u64_u32 v[84:85], s[22:23], v50, s26, v[84:85]
	v_mad_i32_i24 v85, v51, s26, v85
	v_lshl_add_u64 v[50:51], v[184:185], 2, v[84:85]
	v_add_co_u32_e32 v50, vcc, 0x15c86000, v50
	s_nop 1
	v_addc_co_u32_e32 v51, vcc, 0, v51, vcc
	global_store_dwordx4 v[50:51], v[38:41], off offset:16

; __device__ __forceinline__ unsigned cvt_pk_bf16(float lo, float hi) { unsigned r; asm volatile("v_cvt_pk_bf16_f32 %0, %1, %2" : "=v"(r) : "v"(lo), "v"(hi)); return r; }
;     __device__ __forceinline__ void operator()(const f32x4 (&acc)[2][2][4][2], const Unit& u, int wr, int wc, int fr, int fq) const {
;     ...
;                     const float rsm = RS[16 * m]; const f32x4 g = acc[ai][0][m][n] * rsm, uu = acc[ai][1][m][n] * rsm; f32x4 p1, p2, av;
;                     if (!sample) {
; #pragma unroll
;                         for (int e = 0; e < 4; ++e) { float o1, o2;
;                             if (m == 0) { o1 = bm1[e]; o2 = (fr == 0) ? bm2[e] : bm1[e]; } else { const float gp = acc[ai][0][m > 0 ? m - 1 : 0][n][e] * RS[16 * (m > 0 ? m - 1 : 0)]; o1 = dpp_ror1(gp); o2 = dpp_ror2(gp); }
;                             p1[e] = dpp_shr1(o1, g[e]); p2[e] = dpp_shr2(o2, g[e]); }
;                         if (ai == 0 && wr == 0 && m == 0 && fr < 2 && (u.pm & 7) != 0) {
;                             *(f32x4*)(fix + ((size_t)(72 + u.pm * 2 + fr)) * DFF + j0 + 4 * n) = g; *(f32x4*)(fix + ((size_t)(144 + u.pm * 2 + fr)) * DFF + j0 + 4 * n) = uu; }
;                     } else {
;                         const int t = fr & 7, bs = (r - MP) >> 3; f32x4 s0 = (f32x4){0.f, 0.f, 0.f, 0.f}, s1 = s0;
;                         if (t < 2) { s0 = *(const f32x4*)(st_ffn + ((size_t)bs * 2 + 0) * DFF + j0 + 4 * n); s1 = *(const f32x4*)(st_ffn + ((size_t)bs * 2 + 1) * DFF + j0 + 4 * n); }
; #pragma unroll
;                         for (int e = 0; e < 4; ++e) { const float a1 = dpp_shr1(0.f, g[e]), a2 = dpp_shr2(0.f, g[e]); p1[e] = (t >= 1) ? a1 : s1[e]; p2[e] = (t >= 2) ? a2 : (t == 1 ? s1[e] : s0[e]); }
;                         if (t >= 6) *(f32x4*)(out + O_SFFN + ((size_t)bs * 2 + (t - 6)) * DFF + j0 + 4 * n) = g;
;                     }
;                     const f32x4 gc = bb + w0 * p2 + w1 * p1 + w2 * g;
; #pragma unroll
;                     for (int e = 0; e < 4; ++e) av[e] = silu_e(gc[e]) * uu[e];
;                     if (n == 0) { keep[ai][m].x = cvt_pk_bf16(av[0], av[1]); keep[ai][m].y = cvt_pk_bf16(av[2], av[3]); }
;                     else { u32x4e w; w.x = keep[ai][m].x; w.y = keep[ai][m].y; w.z = cvt_pk_bf16(av[0], av[1]); w.w = cvt_pk_bf16(av[2], av[3]); *(u32x4e*)(ACT + act_off(r, j0)) = w; }
.LBB0_868:
	v_mov_b32_e32 v42, v41
	v_mov_b32_e32 v43, v53
	v_pk_mul_f32 v[42:43], v[80:81], v[42:43]
	v_fma_f32 v41, v75, v55, v79
	v_add_f32_e32 v41, v43, v41
	v_add_f32_e32 v44, v42, v41
	v_mul_f32_e32 v41, 0xbfb8aa3b, v44
	v_exp_f32_e32 v41, v41
	v_mov_b32_e32 v42, v60
	v_mov_b32_e32 v43, v60
	v_pk_mul_f32 v[36:37], v[36:37], v[42:43]
	v_add_f32_e32 v41, 1.0, v41
	v_rcp_f32_e32 v42, v41
	v_mov_b32_e32 v41, v52
	v_pk_mul_f32 v[40:41], v[88:89], v[40:41]
	v_fma_f32 v43, v74, v54, v78
	v_add_f32_e32 v41, v41, v43
	v_add_f32_e32 v43, v40, v41
	v_mul_f32_e32 v40, 0xbfb8aa3b, v43
	v_exp_f32_e32 v40, v40
	v_mul_f32_e32 v41, v44, v42
	v_mul_f32_e32 v37, v37, v41
	v_mov_b32_e32 v41, v51
	v_add_f32_e32 v40, 1.0, v40
	v_rcp_f32_e32 v42, v40
	v_mov_b32_e32 v40, v39
	v_pk_mul_f32 v[40:41], v[108:109], v[40:41]
	v_fma_f32 v39, v73, v57, v77
	v_add_f32_e32 v39, v41, v39
	v_add_f32_e32 v40, v40, v39
	v_mul_f32_e32 v39, 0xbfb8aa3b, v40
	v_exp_f32_e32 v41, v39
	v_mov_b32_e32 v39, v50
	v_pk_mul_f32 v[38:39], v[86:87], v[38:39]
	v_fma_f32 v44, v72, v56, v76
	v_add_f32_e32 v39, v39, v44
	v_add_f32_e32 v38, v38, v39
	v_mul_f32_e32 v39, 0xbfb8aa3b, v38
	v_exp_f32_e32 v39, v39
	v_add_f32_e32 v41, 1.0, v41
	v_rcp_f32_e32 v41, v41
	v_mov_b32_e32 v61, v60
	v_add_f32_e32 v39, 1.0, v39
	v_rcp_f32_e32 v39, v39
	v_pk_mul_f32 v[34:35], v[34:35], v[60:61]
	v_mul_f32_e32 v40, v40, v41
	v_mul_f32_e32 v35, v35, v40
	v_mul_f32_e32 v38, v38, v39
	v_mul_f32_e32 v34, v34, v38
	v_cvt_pk_bf16_f32 v100, v34, v35
	v_lshrrev_b32_e32 v34, 8, v62
	v_mul_f32_e32 v42, v43, v42
	v_mad_i32_i24 v34, v34, s60, v125
	v_mul_f32_e32 v36, v36, v42
	v_cvt_pk_bf16_f32 v101, v36, v37
	v_ashrrev_i32_e32 v35, 31, v34
	v_mov_b32_e32 v48, v242
	v_lshlrev_b64 v[34:35], 15, v[34:35]
	v_lshlrev_b32_e32 v36, 7, v151
	v_lshl_add_u64 v[34:35], s[40:41], 0, v[34:35]
	v_and_b32_e32 v36, 0x7f80, v36
	v_mov_b32_e32 v37, v179
	v_lshl_add_u64 v[34:35], v[34:35], 0, v[36:37]
	v_mov_b32_e32 v111, v179
	v_lshl_add_u64 v[34:35], v[34:35], 0, v[110:111]
	global_store_dwordx4 v[34:35], v[98:101], off
	v_add_u32_e32 v50, s74, v142
	s_waitcnt lgkmcnt(0)
	v_pk_mul_f32 v[36:37], v[24:25], v[48:49] op_sel_hi:[1,0]
	v_pk_mul_f32 v[34:35], v[22:23], v[48:49] op_sel_hi:[1,0]
	s_and_b64 vcc, exec, s[16:17]
	s_mov_b64 s[18:19], -1
	s_cbranch_vccnz .LBB0_874
	v_add_u32_e32 v38, 0xffffe000, v50
	v_ashrrev_i32_e32 v38, 3, v38
	v_mov_b32_e32 v40, 0
	v_mov_b32_e32 v41, 0
	v_mov_b32_e32 v42, 0
	v_mov_b32_e32 v43, 0
	v_mov_b32_e32 v44, 0
	v_mov_b32_e32 v45, 0
	v_mov_b32_e32 v46, 0
	v_mov_b32_e32 v47, 0
	s_and_saveexec_b64 s[18:19], s[14:15]
	s_cbranch_execz .LBB0_871
	v_mov_b64_e32 v[40:41], s[36:37]
	v_mad_i64_i32 v[40:41], s[20:21], v38, s53, v[40:41]
	v_lshl_add_u64 v[40:41], v[184:185], 2, v[40:41]
	v_add_co_u32_e32 v44, vcc, 0xa000, v40
	s_nop 1
	v_addc_co_u32_e32 v45, vcc, 0, v41, vcc
	global_load_dwordx4 v[40:43], v[40:41], off offset:16
	s_nop 0
	global_load_dwordx4 v[44:47], v[44:45], off offset:3088
.LBB0_871:
	s_or_b64 exec, exec, s[18:19]
	v_mov_b32_dpp v51, v34 row_shr:1 row_mask:0xf bank_mask:0xf bound_ctrl:1
	v_mov_b32_dpp v52, v34 row_shr:2 row_mask:0xf bank_mask:0xf bound_ctrl:1
	v_mov_b32_dpp v53, v35 row_shr:1 row_mask:0xf bank_mask:0xf bound_ctrl:1
	v_mov_b32_dpp v54, v35 row_shr:2 row_mask:0xf bank_mask:0xf bound_ctrl:1
	v_mov_b32_dpp v55, v36 row_shr:1 row_mask:0xf bank_mask:0xf bound_ctrl:1
	v_mov_b32_dpp v56, v36 row_shr:2 row_mask:0xf bank_mask:0xf bound_ctrl:1
	v_mov_b32_dpp v57, v37 row_shr:1 row_mask:0xf bank_mask:0xf bound_ctrl:1
	v_mov_b32_dpp v49, v37 row_shr:2 row_mask:0xf bank_mask:0xf bound_ctrl:1
	s_and_saveexec_b64 s[18:19], s[12:13]
	s_cbranch_execz .LBB0_873
	v_ashrrev_i32_e32 v39, 31, v38
	v_lshl_add_u64 v[38:39], v[38:39], 1, v[178:179]
	v_mov_b64_e32 v[58:59], s[34:35]
	v_mad_u64_u32 v[58:59], s[20:21], v38, s26, v[58:59]
	v_mad_i32_i24 v59, v39, s26, v59
	v_lshl_add_u64 v[38:39], v[184:185], 2, v[58:59]
	v_add_co_u32_e32 v38, vcc, 0x15c86000, v38
	s_nop 1
	v_addc_co_u32_e32 v39, vcc, 0, v39, vcc
	global_store_dwordx4 v[38:39], v[34:37], off offset:16

; __device__ __forceinline__ unsigned cvt_pk_bf16(float lo, float hi) { unsigned r; asm volatile("v_cvt_pk_bf16_f32 %0, %1, %2" : "=v"(r) : "v"(lo), "v"(hi)); return r; }
;     __device__ __forceinline__ void operator()(const f32x4 (&acc)[2][2][4][2], const Unit& u, int wr, int wc, int fr, int fq) const {
;     ...
;                     const float rsm = RS[16 * m]; const f32x4 g = acc[ai][0][m][n] * rsm, uu = acc[ai][1][m][n] * rsm; f32x4 p1, p2, av;
;                     if (!sample) {
; #pragma unroll
;                         for (int e = 0; e < 4; ++e) { float o1, o2;
;                             if (m == 0) { o1 = bm1[e]; o2 = (fr == 0) ? bm2[e] : bm1[e]; } else { const float gp = acc[ai][0][m > 0 ? m - 1 : 0][n][e] * RS[16 * (m > 0 ? m - 1 : 0)]; o1 = dpp_ror1(gp); o2 = dpp_ror2(gp); }
;                             p1[e] = dpp_shr1(o1, g[e]); p2[e] = dpp_shr2(o2, g[e]); }
;                         if (ai == 0 && wr == 0 && m == 0 && fr < 2 && (u.pm & 7) != 0) {
;                             *(f32x4*)(fix + ((size_t)(72 + u.pm * 2 + fr)) * DFF + j0 + 4 * n) = g; *(f32x4*)(fix + ((size_t)(144 + u.pm * 2 + fr)) * DFF + j0 + 4 * n) = uu; }
;                     } else {
;                         const int t = fr & 7, bs = (r - MP) >> 3; f32x4 s0 = (f32x4){0.f, 0.f, 0.f, 0.f}, s1 = s0;
;                         if (t < 2) { s0 = *(const f32x4*)(st_ffn + ((size_t)bs * 2 + 0) * DFF + j0 + 4 * n); s1 = *(const f32x4*)(st_ffn + ((size_t)bs * 2 + 1) * DFF + j0 + 4 * n); }
; #pragma unroll
;                         for (int e = 0; e < 4; ++e) { const float a1 = dpp_shr1(0.f, g[e]), a2 = dpp_shr2(0.f, g[e]); p1[e] = (t >= 1) ? a1 : s1[e]; p2[e] = (t >= 2) ? a2 : (t == 1 ? s1[e] : s0[e]); }
;                         if (t >= 6) *(f32x4*)(out + O_SFFN + ((size_t)bs * 2 + (t - 6)) * DFF + j0 + 4 * n) = g;
;                     }
;                     const f32x4 gc = bb + w0 * p2 + w1 * p1 + w2 * g;
; #pragma unroll
;                     for (int e = 0; e < 4; ++e) av[e] = silu_e(gc[e]) * uu[e];
;                     if (n == 0) { keep[ai][m].x = cvt_pk_bf16(av[0], av[1]); keep[ai][m].y = cvt_pk_bf16(av[2], av[3]); }
;                     else { u32x4e w; w.x = keep[ai][m].x; w.y = keep[ai][m].y; w.z = cvt_pk_bf16(av[0], av[1]); w.w = cvt_pk_bf16(av[2], av[3]); *(u32x4e*)(ACT + act_off(r, j0)) = w; }
.LBB0_874:
	s_and_b64 vcc, exec, s[18:19]
	s_cbranch_vccz .LBB0_876
	v_mov_b32_e32 v41, v241
	v_mov_b32_e32 v38, v179
	v_mov_b32_e32 v44, v179
	v_mov_b32_e32 v39, v179
	v_mov_b32_e32 v45, v179
	s_waitcnt lgkmcnt(0)
	v_mul_f32_e32 v30, v30, v41
	v_mov_b32_e32 v40, v179
	v_mov_b32_e32 v42, v179
	v_mov_b32_dpp v38, v30 row_ror:1 row_mask:0xf bank_mask:0xf
	v_mov_b32_dpp v44, v30 row_ror:2 row_mask:0xf bank_mask:0xf
	v_mul_f32_e32 v30, v31, v41
	v_mov_b32_e32 v43, v179
	v_mov_b32_dpp v38, v34 row_shr:1 row_mask:0xf bank_mask:0xf
	v_mov_b32_dpp v39, v30 row_ror:1 row_mask:0xf bank_mask:0xf
	v_mov_b32_dpp v45, v30 row_ror:2 row_mask:0xf bank_mask:0xf
	v_mul_f32_e32 v30, v32, v41
	v_mov_b32_dpp v44, v34 row_shr:2 row_mask:0xf bank_mask:0xf
	v_mov_b32_dpp v39, v35 row_shr:1 row_mask:0xf bank_mask:0xf
	v_mov_b32_dpp v40, v30 row_ror:1 row_mask:0xf bank_mask:0xf
	v_mov_b32_dpp v42, v30 row_ror:2 row_mask:0xf bank_mask:0xf
	v_mul_f32_e32 v30, v33, v41
	v_mov_b32_e32 v41, v179
	v_mov_b32_dpp v45, v35 row_shr:2 row_mask:0xf bank_mask:0xf
	v_mov_b32_dpp v43, v30 row_ror:2 row_mask:0xf bank_mask:0xf
	v_mov_b32_dpp v41, v30 row_ror:1 row_mask:0xf bank_mask:0xf
	v_mov_b32_dpp v40, v36 row_shr:1 row_mask:0xf bank_mask:0xf
	v_mov_b32_dpp v42, v36 row_shr:2 row_mask:0xf bank_mask:0xf
	v_mov_b32_dpp v41, v37 row_shr:1 row_mask:0xf bank_mask:0xf
	v_mov_b32_dpp v43, v37 row_shr:2 row_mask:0xf bank_mask:0xf
.LBB0_876:
	v_mov_b32_e32 v30, v37
	v_mov_b32_e32 v31, v41
	v_pk_mul_f32 v[30:31], v[80:81], v[30:31]
	v_fma_f32 v32, v75, v43, v79
	v_add_f32_e32 v31, v31, v32
	v_add_f32_e32 v32, v30, v31
	v_mul_f32_e32 v30, 0xbfb8aa3b, v32
	v_exp_f32_e32 v33, v30
	v_mov_b32_e32 v30, v48
	v_mov_b32_e32 v31, v48
	v_pk_mul_f32 v[28:29], v[28:29], v[30:31]
	v_add_f32_e32 v30, 1.0, v33
	v_mov_b32_e32 v37, v40
	v_rcp_f32_e32 v33, v30
	v_pk_mul_f32 v[30:31], v[88:89], v[36:37]
	v_fma_f32 v36, v74, v42, v78
	v_add_f32_e32 v31, v31, v36
	v_add_f32_e32 v36, v30, v31
	v_mul_f32_e32 v30, 0xbfb8aa3b, v36
	v_exp_f32_e32 v30, v30
	v_mul_f32_e32 v31, v32, v33
	v_mul_f32_e32 v29, v29, v31
	v_mov_b32_e32 v31, v39
	v_add_f32_e32 v30, 1.0, v30
	v_rcp_f32_e32 v32, v30
	v_mov_b32_e32 v30, v35
	v_pk_mul_f32 v[30:31], v[108:109], v[30:31]
	v_fma_f32 v33, v73, v45, v77
	v_add_f32_e32 v31, v31, v33
	v_add_f32_e32 v33, v30, v31
	v_mul_f32_e32 v30, 0xbfb8aa3b, v33
	v_mov_b32_e32 v35, v38
	v_exp_f32_e32 v37, v30
	v_pk_mul_f32 v[30:31], v[86:87], v[34:35]
	v_fma_f32 v34, v72, v44, v76
	v_add_f32_e32 v31, v31, v34
	v_add_f32_e32 v30, v30, v31
	v_mul_f32_e32 v31, 0xbfb8aa3b, v30
	v_exp_f32_e32 v31, v31
	v_add_f32_e32 v34, 1.0, v37
	v_rcp_f32_e32 v34, v34
	v_mov_b32_e32 v49, v48
	v_add_f32_e32 v31, 1.0, v31
	v_rcp_f32_e32 v31, v31
	v_pk_mul_f32 v[26:27], v[26:27], v[48:49]
	v_mul_f32_e32 v32, v36, v32
	v_mul_f32_e32 v28, v28, v32
	v_mul_f32_e32 v30, v30, v31
	v_mul_f32_e32 v32, v33, v34
	v_mul_f32_e32 v26, v26, v30
	v_mul_f32_e32 v27, v27, v32
	v_cvt_pk_bf16_f32 v92, v26, v27
	v_lshrrev_b32_e32 v26, 8, v50
	v_mad_i32_i24 v26, v26, s60, v125
	v_cvt_pk_bf16_f32 v93, v28, v29
	v_ashrrev_i32_e32 v27, 31, v26
	v_mov_b32_e32 v40, v243
	v_lshlrev_b64 v[26:27], 15, v[26:27]
	v_lshlrev_b32_e32 v28, 7, v142
	v_lshl_add_u64 v[26:27], s[40:41], 0, v[26:27]
	v_and_b32_e32 v28, 0x7f80, v28
	v_mov_b32_e32 v29, v179
	v_lshl_add_u64 v[26:27], v[26:27], 0, v[28:29]
	v_mov_b32_e32 v111, v179
	v_lshl_add_u64 v[26:27], v[26:27], 0, v[110:111]
	global_store_dwordx4 v[26:27], v[90:93], off
	v_add_u32_e32 v42, s74, v113
	s_waitcnt lgkmcnt(0)
	v_pk_mul_f32 v[28:29], v[12:13], v[40:41] op_sel_hi:[1,0]
	v_pk_mul_f32 v[26:27], v[10:11], v[40:41] op_sel_hi:[1,0]
	s_and_b64 vcc, exec, s[16:17]
	s_mov_b64 s[18:19], -1
	s_cbranch_vccnz .LBB0_882
	v_add_u32_e32 v30, 0xffffe000, v42
	v_ashrrev_i32_e32 v30, 3, v30
	v_mov_b32_e32 v32, 0
	v_mov_b32_e32 v33, 0
	v_mov_b32_e32 v34, 0
	v_mov_b32_e32 v35, 0
	v_mov_b32_e32 v36, 0
	v_mov_b32_e32 v37, 0
	v_mov_b32_e32 v38, 0
	v_mov_b32_e32 v39, 0
	s_and_saveexec_b64 s[18:19], s[14:15]
	s_cbranch_execz .LBB0_879
	v_mov_b64_e32 v[32:33], s[36:37]
	v_mad_i64_i32 v[32:33], s[20:21], v30, s53, v[32:33]
	v_lshl_add_u64 v[32:33], v[184:185], 2, v[32:33]
	v_add_co_u32_e32 v36, vcc, 0xa000, v32
	s_nop 1
	v_addc_co_u32_e32 v37, vcc, 0, v33, vcc
	global_load_dwordx4 v[32:35], v[32:33], off offset:16
	s_nop 0
	global_load_dwordx4 v[36:39], v[36:37], off offset:3088
.LBB0_879:
	s_or_b64 exec, exec, s[18:19]
	v_mov_b32_dpp v43, v26 row_shr:1 row_mask:0xf bank_mask:0xf bound_ctrl:1
	v_mov_b32_dpp v44, v26 row_shr:2 row_mask:0xf bank_mask:0xf bound_ctrl:1
	v_mov_b32_dpp v45, v27 row_shr:1 row_mask:0xf bank_mask:0xf bound_ctrl:1
	v_mov_b32_dpp v46, v27 row_shr:2 row_mask:0xf bank_mask:0xf bound_ctrl:1
	v_mov_b32_dpp v47, v28 row_shr:1 row_mask:0xf bank_mask:0xf bound_ctrl:1
	v_mov_b32_dpp v48, v28 row_shr:2 row_mask:0xf bank_mask:0xf bound_ctrl:1
	v_mov_b32_dpp v49, v29 row_shr:1 row_mask:0xf bank_mask:0xf bound_ctrl:1
	v_mov_b32_dpp v41, v29 row_shr:2 row_mask:0xf bank_mask:0xf bound_ctrl:1
	s_and_saveexec_b64 s[18:19], s[12:13]
	s_cbranch_execz .LBB0_881
	v_ashrrev_i32_e32 v31, 31, v30
	v_lshl_add_u64 v[30:31], v[30:31], 1, v[178:179]
	v_mov_b64_e32 v[50:51], s[34:35]
	v_mad_u64_u32 v[50:51], s[20:21], v30, s26, v[50:51]
	v_mad_i32_i24 v51, v31, s26, v51
	v_lshl_add_u64 v[30:31], v[184:185], 2, v[50:51]
	v_add_co_u32_e32 v30, vcc, 0x15c86000, v30
	s_nop 1
	v_addc_co_u32_e32 v31, vcc, 0, v31, vcc
	global_store_dwordx4 v[30:31], v[26:29], off offset:16

; __device__ __forceinline__ unsigned cvt_pk_bf16(float lo, float hi) { unsigned r; asm volatile("v_cvt_pk_bf16_f32 %0, %1, %2" : "=v"(r) : "v"(lo), "v"(hi)); return r; }
;     __device__ __forceinline__ void operator()(const f32x4 (&acc)[2][2][4][2], const Unit& u, int wr, int wc, int fr, int fq) const {
;     ...
;                     const float rsm = RS[16 * m]; const f32x4 g = acc[ai][0][m][n] * rsm, uu = acc[ai][1][m][n] * rsm; f32x4 p1, p2, av;
;                     if (!sample) {
; #pragma unroll
;                         for (int e = 0; e < 4; ++e) { float o1, o2;
;                             if (m == 0) { o1 = bm1[e]; o2 = (fr == 0) ? bm2[e] : bm1[e]; } else { const float gp = acc[ai][0][m > 0 ? m - 1 : 0][n][e] * RS[16 * (m > 0 ? m - 1 : 0)]; o1 = dpp_ror1(gp); o2 = dpp_ror2(gp); }
;                             p1[e] = dpp_shr1(o1, g[e]); p2[e] = dpp_shr2(o2, g[e]); }
;                         if (ai == 0 && wr == 0 && m == 0 && fr < 2 && (u.pm & 7) != 0) {
;                             *(f32x4*)(fix + ((size_t)(72 + u.pm * 2 + fr)) * DFF + j0 + 4 * n) = g; *(f32x4*)(fix + ((size_t)(144 + u.pm * 2 + fr)) * DFF + j0 + 4 * n) = uu; }
;                     } else {
;                         const int t = fr & 7, bs = (r - MP) >> 3; f32x4 s0 = (f32x4){0.f, 0.f, 0.f, 0.f}, s1 = s0;
;                         if (t < 2) { s0 = *(const f32x4*)(st_ffn + ((size_t)bs * 2 + 0) * DFF + j0 + 4 * n); s1 = *(const f32x4*)(st_ffn + ((size_t)bs * 2 + 1) * DFF + j0 + 4 * n); }
; #pragma unroll
;                         for (int e = 0; e < 4; ++e) { const float a1 = dpp_shr1(0.f, g[e]), a2 = dpp_shr2(0.f, g[e]); p1[e] = (t >= 1) ? a1 : s1[e]; p2[e] = (t >= 2) ? a2 : (t == 1 ? s1[e] : s0[e]); }
;                         if (t >= 6) *(f32x4*)(out + O_SFFN + ((size_t)bs * 2 + (t - 6)) * DFF + j0 + 4 * n) = g;
;                     }
;                     const f32x4 gc = bb + w0 * p2 + w1 * p1 + w2 * g;
; #pragma unroll
;                     for (int e = 0; e < 4; ++e) av[e] = silu_e(gc[e]) * uu[e];
;                     if (n == 0) { keep[ai][m].x = cvt_pk_bf16(av[0], av[1]); keep[ai][m].y = cvt_pk_bf16(av[2], av[3]); }
;                     else { u32x4e w; w.x = keep[ai][m].x; w.y = keep[ai][m].y; w.z = cvt_pk_bf16(av[0], av[1]); w.w = cvt_pk_bf16(av[2], av[3]); *(u32x4e*)(ACT + act_off(r, j0)) = w; }
.LBB0_882:
	s_and_b64 vcc, exec, s[18:19]
	s_cbranch_vccz .LBB0_884
	v_mov_b32_e32 v33, v242
	v_mov_b32_e32 v30, v179
	v_mov_b32_e32 v36, v179
	v_mov_b32_e32 v31, v179
	v_mov_b32_e32 v37, v179
	s_waitcnt lgkmcnt(0)
	v_mul_f32_e32 v22, v22, v33
	v_mov_b32_e32 v32, v179
	v_mov_b32_e32 v34, v179
	v_mov_b32_dpp v30, v22 row_ror:1 row_mask:0xf bank_mask:0xf
	v_mov_b32_dpp v36, v22 row_ror:2 row_mask:0xf bank_mask:0xf
	v_mul_f32_e32 v22, v23, v33
	v_mov_b32_e32 v35, v179
	v_mov_b32_dpp v30, v26 row_shr:1 row_mask:0xf bank_mask:0xf
	v_mov_b32_dpp v31, v22 row_ror:1 row_mask:0xf bank_mask:0xf
	v_mov_b32_dpp v37, v22 row_ror:2 row_mask:0xf bank_mask:0xf
	v_mul_f32_e32 v22, v24, v33
	v_mov_b32_dpp v36, v26 row_shr:2 row_mask:0xf bank_mask:0xf
	v_mov_b32_dpp v31, v27 row_shr:1 row_mask:0xf bank_mask:0xf
	v_mov_b32_dpp v32, v22 row_ror:1 row_mask:0xf bank_mask:0xf
	v_mov_b32_dpp v34, v22 row_ror:2 row_mask:0xf bank_mask:0xf
	v_mul_f32_e32 v22, v25, v33
	v_mov_b32_e32 v33, v179
	v_mov_b32_dpp v37, v27 row_shr:2 row_mask:0xf bank_mask:0xf
	v_mov_b32_dpp v35, v22 row_ror:2 row_mask:0xf bank_mask:0xf
	v_mov_b32_dpp v33, v22 row_ror:1 row_mask:0xf bank_mask:0xf
	v_mov_b32_dpp v32, v28 row_shr:1 row_mask:0xf bank_mask:0xf
	v_mov_b32_dpp v34, v28 row_shr:2 row_mask:0xf bank_mask:0xf
	v_mov_b32_dpp v33, v29 row_shr:1 row_mask:0xf bank_mask:0xf
	v_mov_b32_dpp v35, v29 row_shr:2 row_mask:0xf bank_mask:0xf
.LBB0_884:
	v_mov_b32_e32 v22, v29
	v_mov_b32_e32 v23, v33
	v_pk_mul_f32 v[22:23], v[80:81], v[22:23]
	v_fma_f32 v24, v75, v35, v79
	v_add_f32_e32 v23, v23, v24
	v_add_f32_e32 v24, v22, v23
	v_mul_f32_e32 v22, 0xbfb8aa3b, v24
	v_exp_f32_e32 v25, v22
	v_mov_b32_e32 v22, v40
	v_mov_b32_e32 v23, v40
	v_pk_mul_f32 v[20:21], v[20:21], v[22:23]
	v_add_f32_e32 v22, 1.0, v25
	v_mov_b32_e32 v29, v32
	v_rcp_f32_e32 v25, v22
	v_pk_mul_f32 v[22:23], v[88:89], v[28:29]
	v_fma_f32 v28, v74, v34, v78
	v_add_f32_e32 v23, v23, v28
	v_add_f32_e32 v28, v22, v23
	v_mul_f32_e32 v22, 0xbfb8aa3b, v28
	v_exp_f32_e32 v22, v22
	v_mul_f32_e32 v23, v24, v25
	v_mul_f32_e32 v21, v21, v23
	v_mov_b32_e32 v23, v31
	v_add_f32_e32 v22, 1.0, v22
	v_rcp_f32_e32 v24, v22
	v_mov_b32_e32 v22, v27
	v_pk_mul_f32 v[22:23], v[108:109], v[22:23]
	v_fma_f32 v25, v73, v37, v77
	v_add_f32_e32 v23, v23, v25
	v_add_f32_e32 v25, v22, v23
	v_mul_f32_e32 v22, 0xbfb8aa3b, v25
	v_mov_b32_e32 v27, v30
	v_exp_f32_e32 v29, v22
	v_pk_mul_f32 v[22:23], v[86:87], v[26:27]
	v_fma_f32 v26, v72, v36, v76
	v_add_f32_e32 v23, v23, v26
	v_add_f32_e32 v22, v22, v23
	v_mul_f32_e32 v23, 0xbfb8aa3b, v22
	v_exp_f32_e32 v23, v23
	v_add_f32_e32 v26, 1.0, v29
	v_rcp_f32_e32 v26, v26
	v_mov_b32_e32 v41, v40
	v_add_f32_e32 v23, 1.0, v23
	v_rcp_f32_e32 v23, v23
	v_pk_mul_f32 v[18:19], v[18:19], v[40:41]
	v_mul_f32_e32 v24, v28, v24
	v_mul_f32_e32 v20, v20, v24
	v_mul_f32_e32 v22, v22, v23
	v_mul_f32_e32 v24, v25, v26
	v_mul_f32_e32 v18, v18, v22
	v_mul_f32_e32 v19, v19, v24
	v_cvt_pk_bf16_f32 v84, v18, v19
	v_lshrrev_b32_e32 v18, 8, v42
	v_cvt_pk_bf16_f32 v85, v20, v21
	v_mad_i32_i24 v18, v18, s60, v125
	v_mov_b32_e32 v28, v244
	v_ashrrev_i32_e32 v19, 31, v18
	v_lshlrev_b64 v[18:19], 15, v[18:19]
	v_lshlrev_b32_e32 v20, 7, v113
	v_lshl_add_u64 v[18:19], s[40:41], 0, v[18:19]
	v_and_b32_e32 v20, 0x7f80, v20
	v_mov_b32_e32 v21, v179
	v_lshl_add_u64 v[18:19], v[18:19], 0, v[20:21]
	v_mov_b32_e32 v111, v179
	v_lshl_add_u64 v[18:19], v[18:19], 0, v[110:111]
	v_add_u32_e32 v30, s74, v112
	s_waitcnt lgkmcnt(0)
	v_pk_mul_f32 v[16:17], v[16:17], v[28:29] op_sel_hi:[1,0]
	v_pk_mul_f32 v[14:15], v[14:15], v[28:29] op_sel_hi:[1,0]
	s_and_b64 vcc, exec, s[16:17]
	s_mov_b64 s[16:17], -1
	global_store_dwordx4 v[18:19], v[82:85], off
	s_cbranch_vccnz .LBB0_890
	v_add_u32_e32 v18, 0xffffe000, v30
	v_ashrrev_i32_e32 v18, 3, v18
	v_mov_b32_e32 v20, 0
	v_mov_b32_e32 v21, 0
	v_mov_b32_e32 v22, 0
	v_mov_b32_e32 v23, 0
	v_mov_b32_e32 v24, 0
	v_mov_b32_e32 v25, 0
	v_mov_b32_e32 v26, 0
	v_mov_b32_e32 v27, 0
	s_and_saveexec_b64 s[16:17], s[14:15]
	s_cbranch_execz .LBB0_887
	v_mov_b64_e32 v[20:21], s[36:37]
	v_mad_i64_i32 v[20:21], s[14:15], v18, s53, v[20:21]
	v_lshl_add_u64 v[20:21], v[184:185], 2, v[20:21]
	v_add_co_u32_e32 v24, vcc, 0xa000, v20
	s_nop 1
	v_addc_co_u32_e32 v25, vcc, 0, v21, vcc
	global_load_dwordx4 v[20:23], v[20:21], off offset:16
	s_nop 0
	global_load_dwordx4 v[24:27], v[24:25], off offset:3088
.LBB0_887:
	s_or_b64 exec, exec, s[16:17]
	v_mov_b32_dpp v31, v14 row_shr:1 row_mask:0xf bank_mask:0xf bound_ctrl:1
	v_mov_b32_dpp v32, v14 row_shr:2 row_mask:0xf bank_mask:0xf bound_ctrl:1
	v_mov_b32_dpp v33, v15 row_shr:1 row_mask:0xf bank_mask:0xf bound_ctrl:1
	v_mov_b32_dpp v34, v15 row_shr:2 row_mask:0xf bank_mask:0xf bound_ctrl:1
	v_mov_b32_dpp v35, v16 row_shr:1 row_mask:0xf bank_mask:0xf bound_ctrl:1
	v_mov_b32_dpp v36, v16 row_shr:2 row_mask:0xf bank_mask:0xf bound_ctrl:1
	v_mov_b32_dpp v37, v17 row_shr:1 row_mask:0xf bank_mask:0xf bound_ctrl:1
	v_mov_b32_dpp v29, v17 row_shr:2 row_mask:0xf bank_mask:0xf bound_ctrl:1
	s_and_saveexec_b64 s[14:15], s[12:13]
	s_cbranch_execz .LBB0_889
	v_ashrrev_i32_e32 v19, 31, v18
	v_lshl_add_u64 v[18:19], v[18:19], 1, v[178:179]
	v_mov_b64_e32 v[38:39], s[34:35]
	v_mad_u64_u32 v[38:39], s[12:13], v18, s26, v[38:39]
	v_mad_i32_i24 v39, v19, s26, v39
	v_lshl_add_u64 v[18:19], v[184:185], 2, v[38:39]
	v_add_co_u32_e32 v18, vcc, 0x15c86000, v18
	s_nop 1
	v_addc_co_u32_e32 v19, vcc, 0, v19, vcc
	global_store_dwordx4 v[18:19], v[14:17], off offset:16

; __device__ __forceinline__ float dpp_shr1(float old, float src) { return __builtin_bit_cast(float, __builtin_amdgcn_update_dpp(__builtin_bit_cast(int, old), __builtin_bit_cast(int, src), 0x111, 0xf, 0xf, false)); }
; __device__ __forceinline__ float dpp_shr2(float old, float src) { return __builtin_bit_cast(float, __builtin_amdgcn_update_dpp(__builtin_bit_cast(int, old), __builtin_bit_cast(int, src), 0x112, 0xf, 0xf, false)); }
; __device__ __forceinline__ float dpp_ror1(float src) { return __builtin_bit_cast(float, __builtin_amdgcn_update_dpp(0, __builtin_bit_cast(int, src), 0x121, 0xf, 0xf, false)); }
; __device__ __forceinline__ float dpp_ror2(float src) { return __builtin_bit_cast(float, __builtin_amdgcn_update_dpp(0, __builtin_bit_cast(int, src), 0x122, 0xf, 0xf, false)); }
;     __device__ __forceinline__ void operator()(const f32x4 (&acc)[2][2][4][2], const Unit& u, int wr, int wc, int fr, int fq) const {
;     ...
;                     const float rsm = RS[16 * m]; const f32x4 g = acc[ai][0][m][n] * rsm, uu = acc[ai][1][m][n] * rsm; f32x4 p1, p2, av;
;                     if (!sample) {
; #pragma unroll
;                         for (int e = 0; e < 4; ++e) { float o1, o2;
;                             if (m == 0) { o1 = bm1[e]; o2 = (fr == 0) ? bm2[e] : bm1[e]; } else { const float gp = acc[ai][0][m > 0 ? m - 1 : 0][n][e] * RS[16 * (m > 0 ? m - 1 : 0)]; o1 = dpp_ror1(gp); o2 = dpp_ror2(gp); }
;                             p1[e] = dpp_shr1(o1, g[e]); p2[e] = dpp_shr2(o2, g[e]); }
.LBB0_890:
	s_and_b64 vcc, exec, s[16:17]
	s_cbranch_vccz .LBB0_892
	v_mov_b32_e32 v21, v243
	v_mov_b32_e32 v18, v179
	v_mov_b32_e32 v24, v179
	v_mov_b32_e32 v19, v179
	v_mov_b32_e32 v25, v179
	s_waitcnt lgkmcnt(0)
	v_mul_f32_e32 v10, v10, v21
	v_mov_b32_e32 v20, v179
	v_mov_b32_e32 v22, v179
	v_mov_b32_dpp v18, v10 row_ror:1 row_mask:0xf bank_mask:0xf
	v_mov_b32_dpp v24, v10 row_ror:2 row_mask:0xf bank_mask:0xf
	v_mul_f32_e32 v10, v11, v21
	v_mov_b32_e32 v23, v179
	v_mov_b32_dpp v18, v14 row_shr:1 row_mask:0xf bank_mask:0xf
	v_mov_b32_dpp v19, v10 row_ror:1 row_mask:0xf bank_mask:0xf
	v_mov_b32_dpp v25, v10 row_ror:2 row_mask:0xf bank_mask:0xf
	v_mul_f32_e32 v10, v12, v21
	v_mov_b32_dpp v24, v14 row_shr:2 row_mask:0xf bank_mask:0xf
	v_mov_b32_dpp v19, v15 row_shr:1 row_mask:0xf bank_mask:0xf
	v_mov_b32_dpp v20, v10 row_ror:1 row_mask:0xf bank_mask:0xf
	v_mov_b32_dpp v22, v10 row_ror:2 row_mask:0xf bank_mask:0xf
	v_mul_f32_e32 v10, v13, v21
	v_mov_b32_e32 v21, v179
	v_mov_b32_dpp v25, v15 row_shr:2 row_mask:0xf bank_mask:0xf
	v_mov_b32_dpp v23, v10 row_ror:2 row_mask:0xf bank_mask:0xf
	v_mov_b32_dpp v21, v10 row_ror:1 row_mask:0xf bank_mask:0xf
	v_mov_b32_dpp v20, v16 row_shr:1 row_mask:0xf bank_mask:0xf
	v_mov_b32_dpp v22, v16 row_shr:2 row_mask:0xf bank_mask:0xf
	v_mov_b32_dpp v21, v17 row_shr:1 row_mask:0xf bank_mask:0xf
	v_mov_b32_dpp v23, v17 row_shr:2 row_mask:0xf bank_mask:0xf
